# speedup vs baseline: 1.0497x; 1.0158x over previous
; #define WAIT_V0() asm volatile("s_waitcnt vmcnt(0)" ::: "memory")
; #define SBAR() __builtin_amdgcn_sched_barrier(0)
; template <int EPI>
; DEVI void gemm_tile(const u16* __restrict__ Ab, long lda, const u16* __restrict__ Bb, long ldb, int K, const EpiArgs& e,
;                     bool have0 = false, const u16* __restrict__ nA = nullptr, const u16* __restrict__ nB = nullptr) {
;     ...
;   f32x4 acc[8][4];
; #pragma unroll
;   for (int m = 0; m < 8; ++m)
; #pragma unroll
;     for (int n = 0; n < 4; ++n) acc[m][n] = f32x4{0.f, 0.f, 0.f, 0.f};
;   const int nt = K / BK;
;   if (!have0) GLDS_STAGE(0, 0);
;   WAIT_V0(); __syncthreads();
;   for (int t = 0; t < nt; ++t) {
;     const int cur = t & 1;
;     if (t + 1 < nt) GLDS_STAGE(cur ^ 1, t + 1);
;     else if (nA) {
; #pragma unroll
;       for (int i = 0; i < GL; ++i) {
;         __builtin_amdgcn_global_load_lds((const unsigned*)(nA + (long)i * 64 * lda + toffA), (unsigned*)(g_shm + wid * 1024 + i * 8192), 16, 0, 0);
;         __builtin_amdgcn_global_load_lds((const unsigned*)(nB + (long)i * 64 * ldb + toffB), (unsigned*)(g_shm + TILE_B + wid * 1024 + i * 8192), 16, 0, 0);
;       }
;     }
;     const char* sb = g_shm + cur * STAGE_B;
; #pragma unroll
;     for (int ks = 0; ks < 2; ++ks) {
;       bf16x8 Bf[4];
; #pragma unroll
;       for (int n = 0; n < 4; ++n) Bf[n] = *(const bf16x8*)(sb + b_base + n * 2048 + ks * 1024);
; #pragma unroll
;       for (int mh = 0; mh < 2; ++mh) {
;         bf16x8 At[4];
; #pragma unroll
;         for (int m = 0; m < 4; ++m) At[m] = *(const bf16x8*)(sb + a_base + (mh * 4 + m) * 2048 + ks * 1024);
;         __builtin_amdgcn_s_setprio(1);
; #pragma unroll
;         for (int m = 0; m < 4; ++m)
; #pragma unroll
;           for (int n = 0; n < 4; ++n) acc[mh * 4 + m][n] = __builtin_amdgcn_mfma_f32_16x16x32_bf16(Bf[n], At[m], acc[mh * 4 + m][n], 0, 0, 0);
;         __builtin_amdgcn_s_setprio(0);
;       }
;       SBAR();
;     }
;     if (t + 1 < nt) { WAIT_V0(); __syncthreads(); }
;   }
.LBB0_150:
	s_and_b32 s3, s2, 0x10000
	v_or_b32_e32 v149, s3, v147
	v_add_u32_e32 v169, v149, v148
	v_add_u32_e32 v149, v149, v146
	ds_read_b128 v[150:153], v169 offset:32768
	ds_read_b128 v[154:157], v169 offset:34816
	ds_read_b128 v[158:161], v169 offset:36864
	ds_read_b128 v[162:165], v169 offset:38912
	ds_read_b128 v[170:173], v149
	ds_read_b128 v[174:177], v149 offset:2048
	ds_read_b128 v[214:217], v149 offset:4096
	ds_read_b128 v[218:221], v149 offset:6144
	v_writelane_b32 v240, s4, 0
	v_writelane_b32 v240, s5, 1
	v_writelane_b32 v240, s6, 2
	v_writelane_b32 v240, s7, 3
	v_writelane_b32 v240, s8, 4
	v_writelane_b32 v240, s9, 5
	v_writelane_b32 v240, s10, 6
	v_readfirstlane_b32 s4, v132
	v_readfirstlane_b32 s5, v133
	s_nop 1
	v_subrev_u32_e32 v238, s4, v132
	s_add_u32 s4, s4, s14
	s_addc_u32 s5, s5, s15
	v_readfirstlane_b32 s6, v134
	v_readfirstlane_b32 s7, v135
	s_nop 1
	v_subrev_u32_e32 v239, s6, v134
	s_add_u32 s6, s6, s14
	s_addc_u32 s7, s7, s15
	s_add_u32 s4, s4, s20
	s_addc_u32 s5, s5, s21
	s_add_u32 s6, s6, s24
	s_addc_u32 s7, s7, s25
	v_readfirstlane_b32 s8, v140
	s_nop 3
	s_lshr_b32 s8, s8, 10
	s_mul_i32 s9, s8, 4
	s_mul_i32 s10, s8, 0
	s_add_i32 s10, s10, 16
	s_cmp_ge_u32 s8, 4
	s_cselect_b32 s10, s10, s9
	s_lshr_b32 s9, s8, 1
	s_sub_i32 s10, s10, s9
	s_lshl_b32 s10, s10, 4
	s_mul_hi_i32 s9, s10, 0x800
	s_mul_i32 s10, s10, 0x800
	s_and_b32 s8, s8, 1
	s_lshl_b32 s8, s8, 6
	s_sub_u32 s10, s10, s8
	s_subb_u32 s9, s9, 0
	s_add_u32 s4, s4, s10
	s_addc_u32 s5, s5, s9
	s_add_u32 s6, s6, s10
	s_addc_u32 s7, s7, s9
	s_cmp_eq_u32 s101, 0
	s_cbranch_scc0 .Lkl_150_s1
	v_readfirstlane_b32 s10, v140
	s_nop 3
	s_mul_i32 s8, s10, 8
	s_mul_i32 s9, s10, 0
	s_add_i32 s9, s9, 0x8000
	s_cmp_ge_u32 s10, 0x1000
	s_cselect_b32 s10, s9, s8
	s_xor_b32 s8, s3, 0x10000
	s_add_i32 s10, s10, s8
	s_add_i32 m0, s10, 0x1000
	s_add_u32 s8, s4, 0x1000
	s_addc_u32 s9, s5, 0x0
	global_load_lds_dwordx4 v238, s[8:9] offset:-4096
	s_add_u32 s8, s4, 0xc40
	s_addc_u32 s9, s5, 0x0
	global_load_lds_dwordx4 v238, s[8:9] offset:-3072
.Lkl_150_s1:
	s_cmp_eq_u32 s101, 0
	s_cbranch_scc0 .Lkl_150_s2
	s_add_u32 s8, s4, 0x8800
	s_addc_u32 s9, s5, 0x0
	global_load_lds_dwordx4 v238, s[8:9] offset:-2048
	s_add_u32 s8, s4, 0x8440
	s_addc_u32 s9, s5, 0x0
	global_load_lds_dwordx4 v238, s[8:9] offset:-1024
.Lkl_150_s2:
	s_cmp_eq_u32 s101, 0
	s_cbranch_scc0 .Lkl_150_s3
	s_add_u32 s8, s4, 0x10000
	s_addc_u32 s9, s5, 0x0
	global_load_lds_dwordx4 v238, s[8:9] offset:0
	s_add_u32 s8, s4, 0xfc40
	s_addc_u32 s9, s5, 0x0
	global_load_lds_dwordx4 v238, s[8:9] offset:1024
.Lkl_150_s3:
.Lkl_150:
	s_waitcnt lgkmcnt(3)
	v_mfma_f32_16x16x32_bf16 v[126:129], v[150:153], v[170:173], v[126:129]
	v_mfma_f32_16x16x32_bf16 v[122:125], v[154:157], v[170:173], v[122:125]
	v_mfma_f32_16x16x32_bf16 v[118:121], v[158:161], v[170:173], v[118:121]
	v_mfma_f32_16x16x32_bf16 v[114:117], v[162:165], v[170:173], v[114:117]
	ds_read_b128 v[170:173], v149 offset:8192
	ds_read_b128 v[222:225], v169 offset:33792
	s_cmp_eq_u32 s101, 0
	s_cbranch_scc0 .Lkl_150_s4
	s_add_u32 s8, s4, 0x17800
	s_addc_u32 s9, s5, 0x0
	global_load_lds_dwordx4 v238, s[8:9] offset:2048
	s_add_u32 s8, s4, 0x17440
	s_addc_u32 s9, s5, 0x0
	global_load_lds_dwordx4 v238, s[8:9] offset:3072
.Lkl_150_s4:
	s_waitcnt lgkmcnt(4)
	v_mfma_f32_16x16x32_bf16 v[110:113], v[150:153], v[174:177], v[110:113]
	v_mfma_f32_16x16x32_bf16 v[106:109], v[154:157], v[174:177], v[106:109]
	v_mfma_f32_16x16x32_bf16 v[102:105], v[158:161], v[174:177], v[102:105]
	v_mfma_f32_16x16x32_bf16 v[98:101], v[162:165], v[174:177], v[98:101]
	ds_read_b128 v[174:177], v149 offset:10240
	ds_read_b128 v[226:229], v169 offset:35840
	s_cmp_eq_u32 s101, 0
	s_cbranch_scc0 .Lkl_150_s5
	s_add_i32 m0, s10, 0x9000
	s_add_u32 s8, s6, 0x1000
	s_addc_u32 s9, s7, 0x0
	global_load_lds_dwordx4 v239, s[8:9] offset:-4096
	s_add_u32 s8, s6, 0xc40
	s_addc_u32 s9, s7, 0x0
	global_load_lds_dwordx4 v239, s[8:9] offset:-3072
.Lkl_150_s5:
	s_waitcnt lgkmcnt(5)
	v_mfma_f32_16x16x32_bf16 v[94:97], v[150:153], v[214:217], v[94:97]
	v_mfma_f32_16x16x32_bf16 v[90:93], v[154:157], v[214:217], v[90:93]
	v_mfma_f32_16x16x32_bf16 v[86:89], v[158:161], v[214:217], v[86:89]
	v_mfma_f32_16x16x32_bf16 v[82:85], v[162:165], v[214:217], v[82:85]
	ds_read_b128 v[214:217], v149 offset:12288
	ds_read_b128 v[230:233], v169 offset:37888
	s_cmp_eq_u32 s101, 0
	s_cbranch_scc0 .Lkl_150_s6
	s_add_u32 s8, s6, 0x8800
	s_addc_u32 s9, s7, 0x0
	global_load_lds_dwordx4 v239, s[8:9] offset:-2048
	s_add_u32 s8, s6, 0x8440
	s_addc_u32 s9, s7, 0x0
	global_load_lds_dwordx4 v239, s[8:9] offset:-1024
.Lkl_150_s6:
	s_waitcnt lgkmcnt(6)
	v_mfma_f32_16x16x32_bf16 v[78:81], v[150:153], v[218:221], v[78:81]
	v_mfma_f32_16x16x32_bf16 v[74:77], v[154:157], v[218:221], v[74:77]
	v_mfma_f32_16x16x32_bf16 v[70:73], v[158:161], v[218:221], v[70:73]
	v_mfma_f32_16x16x32_bf16 v[66:69], v[162:165], v[218:221], v[66:69]
	ds_read_b128 v[218:221], v149 offset:14336
	ds_read_b128 v[234:237], v169 offset:39936
	s_cmp_eq_u32 s101, 0
	s_cbranch_scc0 .Lkl_150_s7
	s_add_u32 s8, s6, 0x10000
	s_addc_u32 s9, s7, 0x0
	global_load_lds_dwordx4 v239, s[8:9] offset:0
	s_add_u32 s8, s6, 0xfc40
	s_addc_u32 s9, s7, 0x0
	global_load_lds_dwordx4 v239, s[8:9] offset:1024
.Lkl_150_s7:
	s_waitcnt lgkmcnt(7)
	v_mfma_f32_16x16x32_bf16 v[62:65], v[150:153], v[170:173], v[62:65]
	v_mfma_f32_16x16x32_bf16 v[58:61], v[154:157], v[170:173], v[58:61]
	v_mfma_f32_16x16x32_bf16 v[54:57], v[158:161], v[170:173], v[54:57]
	v_mfma_f32_16x16x32_bf16 v[50:53], v[162:165], v[170:173], v[50:53]
	ds_read_b128 v[170:173], v149 offset:1024
	s_cmp_eq_u32 s101, 0
	s_cbranch_scc0 .Lkl_150_s8
	s_add_u32 s8, s6, 0x17800
	s_addc_u32 s9, s7, 0x0
	global_load_lds_dwordx4 v239, s[8:9] offset:2048
	s_add_u32 s8, s6, 0x17440
	s_addc_u32 s9, s7, 0x0
	global_load_lds_dwordx4 v239, s[8:9] offset:3072
; #define WAIT_V0() asm volatile("s_waitcnt vmcnt(0)" ::: "memory")
; #define SBAR() __builtin_amdgcn_sched_barrier(0)
; template <int EPI>
; DEVI void gemm_tile(const u16* __restrict__ Ab, long lda, const u16* __restrict__ Bb, long ldb, int K, const EpiArgs& e,
;                     bool have0 = false, const u16* __restrict__ nA = nullptr, const u16* __restrict__ nB = nullptr) {
;     ...
;   for (int t = 0; t < nt; ++t) {
;     const int cur = t & 1;
;     if (t + 1 < nt) GLDS_STAGE(cur ^ 1, t + 1);
;     else if (nA) {
; #pragma unroll
;       for (int i = 0; i < GL; ++i) {
;         __builtin_amdgcn_global_load_lds((const unsigned*)(nA + (long)i * 64 * lda + toffA), (unsigned*)(g_shm + wid * 1024 + i * 8192), 16, 0, 0);
;         __builtin_amdgcn_global_load_lds((const unsigned*)(nB + (long)i * 64 * ldb + toffB), (unsigned*)(g_shm + TILE_B + wid * 1024 + i * 8192), 16, 0, 0);
;       }
;     }
;     const char* sb = g_shm + cur * STAGE_B;
; #pragma unroll
;     for (int ks = 0; ks < 2; ++ks) {
;       bf16x8 Bf[4];
; #pragma unroll
;       for (int n = 0; n < 4; ++n) Bf[n] = *(const bf16x8*)(sb + b_base + n * 2048 + ks * 1024);
; #pragma unroll
;       for (int mh = 0; mh < 2; ++mh) {
;         bf16x8 At[4];
; #pragma unroll
;         for (int m = 0; m < 4; ++m) At[m] = *(const bf16x8*)(sb + a_base + (mh * 4 + m) * 2048 + ks * 1024);
;         __builtin_amdgcn_s_setprio(1);
; #pragma unroll
;         for (int m = 0; m < 4; ++m)
; #pragma unroll
;           for (int n = 0; n < 4; ++n) acc[mh * 4 + m][n] = __builtin_amdgcn_mfma_f32_16x16x32_bf16(Bf[n], At[m], acc[mh * 4 + m][n], 0, 0, 0);
;         __builtin_amdgcn_s_setprio(0);
;       }
;       SBAR();
;     }
;     if (t + 1 < nt) { WAIT_V0(); __syncthreads(); }
;   }
.Lkl_150_s8:
	s_waitcnt lgkmcnt(6)
	v_mfma_f32_16x16x32_bf16 v[46:49], v[150:153], v[174:177], v[46:49]
	v_mfma_f32_16x16x32_bf16 v[42:45], v[154:157], v[174:177], v[42:45]
	v_mfma_f32_16x16x32_bf16 v[38:41], v[158:161], v[174:177], v[38:41]
	v_mfma_f32_16x16x32_bf16 v[34:37], v[162:165], v[174:177], v[34:37]
	ds_read_b128 v[174:177], v149 offset:3072
	s_waitcnt lgkmcnt(5)
	v_mfma_f32_16x16x32_bf16 v[30:33], v[150:153], v[214:217], v[30:33]
	v_mfma_f32_16x16x32_bf16 v[26:29], v[154:157], v[214:217], v[26:29]
	v_mfma_f32_16x16x32_bf16 v[22:25], v[158:161], v[214:217], v[22:25]
	v_mfma_f32_16x16x32_bf16 v[18:21], v[162:165], v[214:217], v[18:21]
	ds_read_b128 v[214:217], v149 offset:5120
	s_waitcnt lgkmcnt(4)
	v_mfma_f32_16x16x32_bf16 v[14:17], v[150:153], v[218:221], v[14:17]
	v_mfma_f32_16x16x32_bf16 v[10:13], v[154:157], v[218:221], v[10:13]
	v_mfma_f32_16x16x32_bf16 v[6:9], v[158:161], v[218:221], v[6:9]
	v_mfma_f32_16x16x32_bf16 v[2:5], v[162:165], v[218:221], v[2:5]
	ds_read_b128 v[218:221], v149 offset:7168
	s_waitcnt lgkmcnt(3)
	v_mfma_f32_16x16x32_bf16 v[126:129], v[222:225], v[170:173], v[126:129]
	v_mfma_f32_16x16x32_bf16 v[122:125], v[226:229], v[170:173], v[122:125]
	v_mfma_f32_16x16x32_bf16 v[118:121], v[230:233], v[170:173], v[118:121]
	v_mfma_f32_16x16x32_bf16 v[114:117], v[234:237], v[170:173], v[114:117]
	ds_read_b128 v[170:173], v149 offset:9216
	s_waitcnt lgkmcnt(3)
	v_mfma_f32_16x16x32_bf16 v[110:113], v[222:225], v[174:177], v[110:113]
	v_mfma_f32_16x16x32_bf16 v[106:109], v[226:229], v[174:177], v[106:109]
	v_mfma_f32_16x16x32_bf16 v[102:105], v[230:233], v[174:177], v[102:105]
	v_mfma_f32_16x16x32_bf16 v[98:101], v[234:237], v[174:177], v[98:101]
	ds_read_b128 v[174:177], v149 offset:11264
	s_waitcnt lgkmcnt(3)
	v_mfma_f32_16x16x32_bf16 v[94:97], v[222:225], v[214:217], v[94:97]
	v_mfma_f32_16x16x32_bf16 v[90:93], v[226:229], v[214:217], v[90:93]
	v_mfma_f32_16x16x32_bf16 v[86:89], v[230:233], v[214:217], v[86:89]
	v_mfma_f32_16x16x32_bf16 v[82:85], v[234:237], v[214:217], v[82:85]
	ds_read_b128 v[214:217], v149 offset:13312
	s_waitcnt lgkmcnt(3)
	v_mfma_f32_16x16x32_bf16 v[78:81], v[222:225], v[218:221], v[78:81]
	v_mfma_f32_16x16x32_bf16 v[74:77], v[226:229], v[218:221], v[74:77]
	v_mfma_f32_16x16x32_bf16 v[70:73], v[230:233], v[218:221], v[70:73]
	v_mfma_f32_16x16x32_bf16 v[66:69], v[234:237], v[218:221], v[66:69]
	ds_read_b128 v[218:221], v149 offset:15360
	s_waitcnt lgkmcnt(3)
	v_mfma_f32_16x16x32_bf16 v[62:65], v[222:225], v[170:173], v[62:65]
	v_mfma_f32_16x16x32_bf16 v[58:61], v[226:229], v[170:173], v[58:61]
	v_mfma_f32_16x16x32_bf16 v[54:57], v[230:233], v[170:173], v[54:57]
	v_mfma_f32_16x16x32_bf16 v[50:53], v[234:237], v[170:173], v[50:53]
	s_waitcnt lgkmcnt(2)
	v_mfma_f32_16x16x32_bf16 v[46:49], v[222:225], v[174:177], v[46:49]
	v_mfma_f32_16x16x32_bf16 v[42:45], v[226:229], v[174:177], v[42:45]
	v_mfma_f32_16x16x32_bf16 v[38:41], v[230:233], v[174:177], v[38:41]
	v_mfma_f32_16x16x32_bf16 v[34:37], v[234:237], v[174:177], v[34:37]
	s_waitcnt lgkmcnt(0)
	s_add_i32 s2, s2, 0x10000
	s_waitcnt vmcnt(0)
	s_add_u32 s14, s14, 0x80
	s_addc_u32 s15, s15, 0
	s_cmpk_eq_i32 s14, 0x780
	s_waitcnt vmcnt(0)
	s_barrier
	s_cselect_b32 s100, 1, 0
	s_and_b32 s3, s2, 0x10000
	v_or_b32_e32 v149, s3, v147
	v_add_u32_e32 v169, v149, v148
	v_add_u32_e32 v149, v149, v146
	ds_read_b128 v[150:153], v169 offset:32768
	ds_read_b128 v[154:157], v169 offset:34816
	ds_read_b128 v[158:161], v169 offset:36864
	ds_read_b128 v[162:165], v169 offset:38912
	ds_read_b128 v[170:173], v149
	ds_read_b128 v[174:177], v149 offset:2048
	s_add_u32 s4, s4, 0x80
	s_addc_u32 s5, s5, 0
	s_add_u32 s6, s6, 0x80
	s_addc_u32 s7, s7, 0
	s_cmp_eq_u32 s100, 1
	s_cbranch_scc1 .Lkl_150_s9
	s_cmp_eq_u32 s101, 0
	s_cbranch_scc0 .Lkl_150_s9
	v_readfirstlane_b32 s10, v140
	s_nop 3
	s_mul_i32 s8, s10, 8
	s_mul_i32 s9, s10, 0
	s_add_i32 s9, s9, 0x8000
	s_cmp_ge_u32 s10, 0x1000
	s_cselect_b32 s10, s9, s8
	s_xor_b32 s8, s3, 0x10000
	s_add_i32 s10, s10, s8
	s_add_i32 m0, s10, 0x1000
	s_add_u32 s8, s4, 0x1000
	s_addc_u32 s9, s5, 0x0
	global_load_lds_dwordx4 v238, s[8:9] offset:-4096
	s_add_u32 s8, s4, 0xc40
	s_addc_u32 s9, s5, 0x0
	global_load_lds_dwordx4 v238, s[8:9] offset:-3072
.Lkl_150_s9:
	v_mfma_f32_16x16x32_bf16 v[30:33], v[222:225], v[214:217], v[30:33]
	v_mfma_f32_16x16x32_bf16 v[26:29], v[226:229], v[214:217], v[26:29]
	v_mfma_f32_16x16x32_bf16 v[22:25], v[230:233], v[214:217], v[22:25]
	v_mfma_f32_16x16x32_bf16 v[18:21], v[234:237], v[214:217], v[18:21]
	ds_read_b128 v[214:217], v149 offset:4096
	s_cmp_eq_u32 s100, 1
	s_cbranch_scc1 .Lkl_150_s10
	s_cmp_eq_u32 s101, 0
	s_cbranch_scc0 .Lkl_150_s10
	s_add_u32 s8, s4, 0x8800
	s_addc_u32 s9, s5, 0x0
	global_load_lds_dwordx4 v238, s[8:9] offset:-2048
	s_add_u32 s8, s4, 0x8440
	s_addc_u32 s9, s5, 0x0
	global_load_lds_dwordx4 v238, s[8:9] offset:-1024
.Lkl_150_s10:
	v_mfma_f32_16x16x32_bf16 v[14:17], v[222:225], v[218:221], v[14:17]
	v_mfma_f32_16x16x32_bf16 v[10:13], v[226:229], v[218:221], v[10:13]
	v_mfma_f32_16x16x32_bf16 v[6:9], v[230:233], v[218:221], v[6:9]
	v_mfma_f32_16x16x32_bf16 v[2:5], v[234:237], v[218:221], v[2:5]
	ds_read_b128 v[218:221], v149 offset:6144
	s_cmp_eq_u32 s100, 1
	s_cbranch_scc1 .Lkl_150_s11
	s_cmp_eq_u32 s101, 0
	s_cbranch_scc0 .Lkl_150_s11
	s_add_u32 s8, s4, 0x10000
	s_addc_u32 s9, s5, 0x0
	global_load_lds_dwordx4 v238, s[8:9] offset:0
	s_add_u32 s8, s4, 0xfc40
	s_addc_u32 s9, s5, 0x0
	global_load_lds_dwordx4 v238, s[8:9] offset:1024

; #define WAIT_V0() asm volatile("s_waitcnt vmcnt(0)" ::: "memory")
; #define SBAR() __builtin_amdgcn_sched_barrier(0)
; template <int EPI>
; DEVI void gemm_tile(const u16* __restrict__ Ab, long lda, const u16* __restrict__ Bb, long ldb, int K, const EpiArgs& e,
;                     bool have0 = false, const u16* __restrict__ nA = nullptr, const u16* __restrict__ nB = nullptr) {
;     ...
;   f32x4 acc[8][4];
; #pragma unroll
;   for (int m = 0; m < 8; ++m)
; #pragma unroll
;     for (int n = 0; n < 4; ++n) acc[m][n] = f32x4{0.f, 0.f, 0.f, 0.f};
;   const int nt = K / BK;
;   if (!have0) GLDS_STAGE(0, 0);
;   WAIT_V0(); __syncthreads();
;   for (int t = 0; t < nt; ++t) {
;     const int cur = t & 1;
;     if (t + 1 < nt) GLDS_STAGE(cur ^ 1, t + 1);
;     else if (nA) {
; #pragma unroll
;       for (int i = 0; i < GL; ++i) {
;         __builtin_amdgcn_global_load_lds((const unsigned*)(nA + (long)i * 64 * lda + toffA), (unsigned*)(g_shm + wid * 1024 + i * 8192), 16, 0, 0);
;         __builtin_amdgcn_global_load_lds((const unsigned*)(nB + (long)i * 64 * ldb + toffB), (unsigned*)(g_shm + TILE_B + wid * 1024 + i * 8192), 16, 0, 0);
;       }
;     }
;     const char* sb = g_shm + cur * STAGE_B;
; #pragma unroll
;     for (int ks = 0; ks < 2; ++ks) {
;       bf16x8 Bf[4];
; #pragma unroll
;       for (int n = 0; n < 4; ++n) Bf[n] = *(const bf16x8*)(sb + b_base + n * 2048 + ks * 1024);
; #pragma unroll
;       for (int mh = 0; mh < 2; ++mh) {
;         bf16x8 At[4];
; #pragma unroll
;         for (int m = 0; m < 4; ++m) At[m] = *(const bf16x8*)(sb + a_base + (mh * 4 + m) * 2048 + ks * 1024);
;         __builtin_amdgcn_s_setprio(1);
; #pragma unroll
;         for (int m = 0; m < 4; ++m)
; #pragma unroll
;           for (int n = 0; n < 4; ++n) acc[mh * 4 + m][n] = __builtin_amdgcn_mfma_f32_16x16x32_bf16(Bf[n], At[m], acc[mh * 4 + m][n], 0, 0, 0);
;         __builtin_amdgcn_s_setprio(0);
;       }
;       SBAR();
;     }
;     if (t + 1 < nt) { WAIT_V0(); __syncthreads(); }
;   }
.LBB0_184:
	s_and_b32 s22, s3, 0x10000
	v_or_b32_e32 v150, s22, v149
	v_add_u32_e32 v169, v150, v148
	v_or_b32_e32 v150, s22, v146
	v_add_u32_e32 v178, v150, v147
	ds_read_b128 v[150:153], v169 offset:32768
	ds_read_b128 v[154:157], v169 offset:34816
	ds_read_b128 v[158:161], v169 offset:36864
	ds_read_b128 v[162:165], v169 offset:38912
	ds_read_b128 v[170:173], v178
	ds_read_b128 v[174:177], v178 offset:2048
	ds_read_b128 v[214:217], v178 offset:4096
	ds_read_b128 v[218:221], v178 offset:6144
	v_writelane_b32 v240, s4, 0
	v_writelane_b32 v240, s5, 1
	v_writelane_b32 v240, s6, 2
	v_writelane_b32 v240, s7, 3
	v_writelane_b32 v240, s8, 4
	v_writelane_b32 v240, s9, 5
	v_writelane_b32 v240, s10, 6
	v_readfirstlane_b32 s4, v134
	v_readfirstlane_b32 s5, v135
	s_nop 1
	v_subrev_u32_e32 v238, s4, v134
	s_add_u32 s4, s4, s14
	s_addc_u32 s5, s5, s15
	v_readfirstlane_b32 s6, v136
	v_readfirstlane_b32 s7, v137
	s_nop 1
	v_subrev_u32_e32 v239, s6, v136
	s_add_u32 s6, s6, s14
	s_addc_u32 s7, s7, s15
	s_add_u32 s4, s4, s24
	s_addc_u32 s5, s5, s25
	s_add_u32 s6, s6, 0x1600080
	s_addc_u32 s7, s7, 0
	v_readfirstlane_b32 s8, v143
	s_nop 3
	s_lshr_b32 s8, s8, 10
	s_mul_i32 s9, s8, 4
	s_mul_i32 s10, s8, 0
	s_add_i32 s10, s10, 16
	s_cmp_ge_u32 s8, 4
	s_cselect_b32 s10, s10, s9
	s_lshr_b32 s9, s8, 1
	s_sub_i32 s10, s10, s9
	s_lshl_b32 s10, s10, 4
	s_mul_hi_i32 s9, s10, 0x1600
	s_mul_i32 s10, s10, 0x1600
	s_and_b32 s8, s8, 1
	s_lshl_b32 s8, s8, 6
	s_sub_u32 s10, s10, s8
	s_subb_u32 s9, s9, 0
	s_add_u32 s4, s4, s10
	s_addc_u32 s5, s5, s9
	s_add_u32 s6, s6, s10
	s_addc_u32 s7, s7, s9
	s_cmp_eq_u32 s101, 0
	s_cbranch_scc0 .Lkl_184_s1
	v_readfirstlane_b32 s10, v143
	s_nop 3
	s_mul_i32 s8, s10, 8
	s_mul_i32 s9, s10, 0
	s_add_i32 s9, s9, 0x8000
	s_cmp_ge_u32 s10, 0x1000
	s_cselect_b32 s10, s9, s8
	s_xor_b32 s8, s22, 0x10000
	s_add_i32 s10, s10, s8
	s_add_i32 m0, s10, 0x1000
	s_add_u32 s8, s4, 0x1000
	s_addc_u32 s9, s5, 0x0
	global_load_lds_dwordx4 v238, s[8:9] offset:-4096
	s_add_u32 s8, s4, 0xc40
	s_addc_u32 s9, s5, 0x0
	global_load_lds_dwordx4 v238, s[8:9] offset:-3072
.Lkl_184_s1:
	s_cmp_eq_u32 s101, 0
	s_cbranch_scc0 .Lkl_184_s2
	s_add_u32 s8, s4, 0x16800
	s_addc_u32 s9, s5, 0x0
	global_load_lds_dwordx4 v238, s[8:9] offset:-2048
	s_add_u32 s8, s4, 0x16440
	s_addc_u32 s9, s5, 0x0
	global_load_lds_dwordx4 v238, s[8:9] offset:-1024
.Lkl_184_s2:
	s_cmp_eq_u32 s101, 0
	s_cbranch_scc0 .Lkl_184_s3
	s_add_u32 s8, s4, 0x2c000
	s_addc_u32 s9, s5, 0x0
	global_load_lds_dwordx4 v238, s[8:9] offset:0
	s_add_u32 s8, s4, 0x2bc40
	s_addc_u32 s9, s5, 0x0
	global_load_lds_dwordx4 v238, s[8:9] offset:1024
.Lkl_184_s3:
.Lkl_184:
	s_waitcnt lgkmcnt(3)
	v_mfma_f32_16x16x32_bf16 v[126:129], v[150:153], v[170:173], v[126:129]
	v_mfma_f32_16x16x32_bf16 v[122:125], v[154:157], v[170:173], v[122:125]
	v_mfma_f32_16x16x32_bf16 v[118:121], v[158:161], v[170:173], v[118:121]
	v_mfma_f32_16x16x32_bf16 v[114:117], v[162:165], v[170:173], v[114:117]
	ds_read_b128 v[170:173], v178 offset:8192
	ds_read_b128 v[222:225], v169 offset:33792
	s_cmp_eq_u32 s101, 0
	s_cbranch_scc0 .Lkl_184_s4
	s_add_u32 s8, s4, 0x41800
	s_addc_u32 s9, s5, 0x0
	global_load_lds_dwordx4 v238, s[8:9] offset:2048
	s_add_u32 s8, s4, 0x41440
	s_addc_u32 s9, s5, 0x0
	global_load_lds_dwordx4 v238, s[8:9] offset:3072
.Lkl_184_s4:
	s_waitcnt lgkmcnt(4)
	v_mfma_f32_16x16x32_bf16 v[110:113], v[150:153], v[174:177], v[110:113]
	v_mfma_f32_16x16x32_bf16 v[106:109], v[154:157], v[174:177], v[106:109]
	v_mfma_f32_16x16x32_bf16 v[102:105], v[158:161], v[174:177], v[102:105]
	v_mfma_f32_16x16x32_bf16 v[98:101], v[162:165], v[174:177], v[98:101]
	ds_read_b128 v[174:177], v178 offset:10240
	ds_read_b128 v[226:229], v169 offset:35840
	s_cmp_eq_u32 s101, 0
	s_cbranch_scc0 .Lkl_184_s5
	s_add_i32 m0, s10, 0x9000
	s_add_u32 s8, s6, 0x1000
	s_addc_u32 s9, s7, 0x0
	global_load_lds_dwordx4 v239, s[8:9] offset:-4096
	s_add_u32 s8, s6, 0xc40
	s_addc_u32 s9, s7, 0x0
	global_load_lds_dwordx4 v239, s[8:9] offset:-3072
.Lkl_184_s5:
	s_waitcnt lgkmcnt(5)
	v_mfma_f32_16x16x32_bf16 v[94:97], v[150:153], v[214:217], v[94:97]
	v_mfma_f32_16x16x32_bf16 v[90:93], v[154:157], v[214:217], v[90:93]
	v_mfma_f32_16x16x32_bf16 v[86:89], v[158:161], v[214:217], v[86:89]
	v_mfma_f32_16x16x32_bf16 v[82:85], v[162:165], v[214:217], v[82:85]
	ds_read_b128 v[214:217], v178 offset:12288
	ds_read_b128 v[230:233], v169 offset:37888
	s_cmp_eq_u32 s101, 0
	s_cbranch_scc0 .Lkl_184_s6
	s_add_u32 s8, s6, 0x16800
	s_addc_u32 s9, s7, 0x0
	global_load_lds_dwordx4 v239, s[8:9] offset:-2048
	s_add_u32 s8, s6, 0x16440
	s_addc_u32 s9, s7, 0x0
	global_load_lds_dwordx4 v239, s[8:9] offset:-1024
.Lkl_184_s6:
	s_waitcnt lgkmcnt(6)
	v_mfma_f32_16x16x32_bf16 v[78:81], v[150:153], v[218:221], v[78:81]
	v_mfma_f32_16x16x32_bf16 v[74:77], v[154:157], v[218:221], v[74:77]
	v_mfma_f32_16x16x32_bf16 v[70:73], v[158:161], v[218:221], v[70:73]
	v_mfma_f32_16x16x32_bf16 v[66:69], v[162:165], v[218:221], v[66:69]
	ds_read_b128 v[218:221], v178 offset:14336
	ds_read_b128 v[234:237], v169 offset:39936
	s_cmp_eq_u32 s101, 0
	s_cbranch_scc0 .Lkl_184_s7
	s_add_u32 s8, s6, 0x2c000
	s_addc_u32 s9, s7, 0x0
	global_load_lds_dwordx4 v239, s[8:9] offset:0
	s_add_u32 s8, s6, 0x2bc40
	s_addc_u32 s9, s7, 0x0
	global_load_lds_dwordx4 v239, s[8:9] offset:1024
.Lkl_184_s7:
	s_waitcnt lgkmcnt(7)
	v_mfma_f32_16x16x32_bf16 v[62:65], v[150:153], v[170:173], v[62:65]
	v_mfma_f32_16x16x32_bf16 v[58:61], v[154:157], v[170:173], v[58:61]
	v_mfma_f32_16x16x32_bf16 v[54:57], v[158:161], v[170:173], v[54:57]
	v_mfma_f32_16x16x32_bf16 v[50:53], v[162:165], v[170:173], v[50:53]
	ds_read_b128 v[170:173], v178 offset:1024
	s_cmp_eq_u32 s101, 0
	s_cbranch_scc0 .Lkl_184_s8
	s_add_u32 s8, s6, 0x41800
	s_addc_u32 s9, s7, 0x0
	global_load_lds_dwordx4 v239, s[8:9] offset:2048
	s_add_u32 s8, s6, 0x41440
	s_addc_u32 s9, s7, 0x0
	global_load_lds_dwordx4 v239, s[8:9] offset:3072
; #define WAIT_V0() asm volatile("s_waitcnt vmcnt(0)" ::: "memory")
; #define SBAR() __builtin_amdgcn_sched_barrier(0)
; template <int EPI>
; DEVI void gemm_tile(const u16* __restrict__ Ab, long lda, const u16* __restrict__ Bb, long ldb, int K, const EpiArgs& e,
;                     bool have0 = false, const u16* __restrict__ nA = nullptr, const u16* __restrict__ nB = nullptr) {
;     ...
;   for (int t = 0; t < nt; ++t) {
;     const int cur = t & 1;
;     if (t + 1 < nt) GLDS_STAGE(cur ^ 1, t + 1);
;     else if (nA) {
; #pragma unroll
;       for (int i = 0; i < GL; ++i) {
;         __builtin_amdgcn_global_load_lds((const unsigned*)(nA + (long)i * 64 * lda + toffA), (unsigned*)(g_shm + wid * 1024 + i * 8192), 16, 0, 0);
;         __builtin_amdgcn_global_load_lds((const unsigned*)(nB + (long)i * 64 * ldb + toffB), (unsigned*)(g_shm + TILE_B + wid * 1024 + i * 8192), 16, 0, 0);
;       }
;     }
;     const char* sb = g_shm + cur * STAGE_B;
; #pragma unroll
;     for (int ks = 0; ks < 2; ++ks) {
;       bf16x8 Bf[4];
; #pragma unroll
;       for (int n = 0; n < 4; ++n) Bf[n] = *(const bf16x8*)(sb + b_base + n * 2048 + ks * 1024);
; #pragma unroll
;       for (int mh = 0; mh < 2; ++mh) {
;         bf16x8 At[4];
; #pragma unroll
;         for (int m = 0; m < 4; ++m) At[m] = *(const bf16x8*)(sb + a_base + (mh * 4 + m) * 2048 + ks * 1024);
;         __builtin_amdgcn_s_setprio(1);
; #pragma unroll
;         for (int m = 0; m < 4; ++m)
; #pragma unroll
;           for (int n = 0; n < 4; ++n) acc[mh * 4 + m][n] = __builtin_amdgcn_mfma_f32_16x16x32_bf16(Bf[n], At[m], acc[mh * 4 + m][n], 0, 0, 0);
;         __builtin_amdgcn_s_setprio(0);
;       }
;       SBAR();
;     }
;     if (t + 1 < nt) { WAIT_V0(); __syncthreads(); }
;   }
.Lkl_184_s8:
	s_waitcnt lgkmcnt(6)
	v_mfma_f32_16x16x32_bf16 v[46:49], v[150:153], v[174:177], v[46:49]
	v_mfma_f32_16x16x32_bf16 v[42:45], v[154:157], v[174:177], v[42:45]
	v_mfma_f32_16x16x32_bf16 v[38:41], v[158:161], v[174:177], v[38:41]
	v_mfma_f32_16x16x32_bf16 v[34:37], v[162:165], v[174:177], v[34:37]
	ds_read_b128 v[174:177], v178 offset:3072
	s_waitcnt lgkmcnt(5)
	v_mfma_f32_16x16x32_bf16 v[30:33], v[150:153], v[214:217], v[30:33]
	v_mfma_f32_16x16x32_bf16 v[26:29], v[154:157], v[214:217], v[26:29]
	v_mfma_f32_16x16x32_bf16 v[22:25], v[158:161], v[214:217], v[22:25]
	v_mfma_f32_16x16x32_bf16 v[18:21], v[162:165], v[214:217], v[18:21]
	ds_read_b128 v[214:217], v178 offset:5120
	s_waitcnt lgkmcnt(4)
	v_mfma_f32_16x16x32_bf16 v[14:17], v[150:153], v[218:221], v[14:17]
	v_mfma_f32_16x16x32_bf16 v[10:13], v[154:157], v[218:221], v[10:13]
	v_mfma_f32_16x16x32_bf16 v[6:9], v[158:161], v[218:221], v[6:9]
	v_mfma_f32_16x16x32_bf16 v[2:5], v[162:165], v[218:221], v[2:5]
	ds_read_b128 v[218:221], v178 offset:7168
	s_waitcnt lgkmcnt(3)
	v_mfma_f32_16x16x32_bf16 v[126:129], v[222:225], v[170:173], v[126:129]
	v_mfma_f32_16x16x32_bf16 v[122:125], v[226:229], v[170:173], v[122:125]
	v_mfma_f32_16x16x32_bf16 v[118:121], v[230:233], v[170:173], v[118:121]
	v_mfma_f32_16x16x32_bf16 v[114:117], v[234:237], v[170:173], v[114:117]
	ds_read_b128 v[170:173], v178 offset:9216
	s_waitcnt lgkmcnt(3)
	v_mfma_f32_16x16x32_bf16 v[110:113], v[222:225], v[174:177], v[110:113]
	v_mfma_f32_16x16x32_bf16 v[106:109], v[226:229], v[174:177], v[106:109]
	v_mfma_f32_16x16x32_bf16 v[102:105], v[230:233], v[174:177], v[102:105]
	v_mfma_f32_16x16x32_bf16 v[98:101], v[234:237], v[174:177], v[98:101]
	ds_read_b128 v[174:177], v178 offset:11264
	s_waitcnt lgkmcnt(3)
	v_mfma_f32_16x16x32_bf16 v[94:97], v[222:225], v[214:217], v[94:97]
	v_mfma_f32_16x16x32_bf16 v[90:93], v[226:229], v[214:217], v[90:93]
	v_mfma_f32_16x16x32_bf16 v[86:89], v[230:233], v[214:217], v[86:89]
	v_mfma_f32_16x16x32_bf16 v[82:85], v[234:237], v[214:217], v[82:85]
	ds_read_b128 v[214:217], v178 offset:13312
	s_waitcnt lgkmcnt(3)
	v_mfma_f32_16x16x32_bf16 v[78:81], v[222:225], v[218:221], v[78:81]
	v_mfma_f32_16x16x32_bf16 v[74:77], v[226:229], v[218:221], v[74:77]
	v_mfma_f32_16x16x32_bf16 v[70:73], v[230:233], v[218:221], v[70:73]
	v_mfma_f32_16x16x32_bf16 v[66:69], v[234:237], v[218:221], v[66:69]
	ds_read_b128 v[218:221], v178 offset:15360
	s_waitcnt lgkmcnt(3)
	v_mfma_f32_16x16x32_bf16 v[62:65], v[222:225], v[170:173], v[62:65]
	v_mfma_f32_16x16x32_bf16 v[58:61], v[226:229], v[170:173], v[58:61]
	v_mfma_f32_16x16x32_bf16 v[54:57], v[230:233], v[170:173], v[54:57]
	v_mfma_f32_16x16x32_bf16 v[50:53], v[234:237], v[170:173], v[50:53]
	s_waitcnt lgkmcnt(2)
	v_mfma_f32_16x16x32_bf16 v[46:49], v[222:225], v[174:177], v[46:49]
	v_mfma_f32_16x16x32_bf16 v[42:45], v[226:229], v[174:177], v[42:45]
	v_mfma_f32_16x16x32_bf16 v[38:41], v[230:233], v[174:177], v[38:41]
	v_mfma_f32_16x16x32_bf16 v[34:37], v[234:237], v[174:177], v[34:37]
	s_waitcnt lgkmcnt(0)
	s_waitcnt vmcnt(0)
	s_add_u32 s14, s14, 0x80
	s_addc_u32 s15, s15, 0
	s_add_i32 s3, s3, 0x10000
	s_cmpk_eq_i32 s14, 0x1580
	s_waitcnt vmcnt(0)
	s_barrier
	s_cselect_b32 s100, 1, 0
	s_and_b32 s22, s3, 0x10000
	v_or_b32_e32 v150, s22, v149
	v_add_u32_e32 v169, v150, v148
	v_or_b32_e32 v150, s22, v146
	v_add_u32_e32 v178, v150, v147
	ds_read_b128 v[150:153], v169 offset:32768
	ds_read_b128 v[154:157], v169 offset:34816
	ds_read_b128 v[158:161], v169 offset:36864
	ds_read_b128 v[162:165], v169 offset:38912
	ds_read_b128 v[170:173], v178
	ds_read_b128 v[174:177], v178 offset:2048
	s_add_u32 s4, s4, 0x80
	s_addc_u32 s5, s5, 0
	s_add_u32 s6, s6, 0x80
	s_addc_u32 s7, s7, 0
	s_cmp_eq_u32 s100, 1
	s_cbranch_scc1 .Lkl_184_s9
	s_cmp_eq_u32 s101, 0
	s_cbranch_scc0 .Lkl_184_s9
	v_readfirstlane_b32 s10, v143
	s_nop 3
	s_mul_i32 s8, s10, 8
	s_mul_i32 s9, s10, 0
	s_add_i32 s9, s9, 0x8000
	s_cmp_ge_u32 s10, 0x1000
	s_cselect_b32 s10, s9, s8
	s_xor_b32 s8, s22, 0x10000
	s_add_i32 s10, s10, s8
	s_add_i32 m0, s10, 0x1000
	s_add_u32 s8, s4, 0x1000
	s_addc_u32 s9, s5, 0x0
	global_load_lds_dwordx4 v238, s[8:9] offset:-4096
	s_add_u32 s8, s4, 0xc40
	s_addc_u32 s9, s5, 0x0
	global_load_lds_dwordx4 v238, s[8:9] offset:-3072
.Lkl_184_s9:
	v_mfma_f32_16x16x32_bf16 v[30:33], v[222:225], v[214:217], v[30:33]
	v_mfma_f32_16x16x32_bf16 v[26:29], v[226:229], v[214:217], v[26:29]
	v_mfma_f32_16x16x32_bf16 v[22:25], v[230:233], v[214:217], v[22:25]
	v_mfma_f32_16x16x32_bf16 v[18:21], v[234:237], v[214:217], v[18:21]
	ds_read_b128 v[214:217], v178 offset:4096
	s_cmp_eq_u32 s100, 1
	s_cbranch_scc1 .Lkl_184_s10
	s_cmp_eq_u32 s101, 0
	s_cbranch_scc0 .Lkl_184_s10
	s_add_u32 s8, s4, 0x16800
	s_addc_u32 s9, s5, 0x0
	global_load_lds_dwordx4 v238, s[8:9] offset:-2048
	s_add_u32 s8, s4, 0x16440
	s_addc_u32 s9, s5, 0x0
	global_load_lds_dwordx4 v238, s[8:9] offset:-1024
.Lkl_184_s10:
	v_mfma_f32_16x16x32_bf16 v[14:17], v[222:225], v[218:221], v[14:17]
	v_mfma_f32_16x16x32_bf16 v[10:13], v[226:229], v[218:221], v[10:13]
	v_mfma_f32_16x16x32_bf16 v[6:9], v[230:233], v[218:221], v[6:9]
	v_mfma_f32_16x16x32_bf16 v[2:5], v[234:237], v[218:221], v[2:5]
	ds_read_b128 v[218:221], v178 offset:6144
	s_cmp_eq_u32 s100, 1
	s_cbranch_scc1 .Lkl_184_s11
	s_cmp_eq_u32 s101, 0
	s_cbranch_scc0 .Lkl_184_s11
	s_add_u32 s8, s4, 0x2c000
	s_addc_u32 s9, s5, 0x0
	global_load_lds_dwordx4 v238, s[8:9] offset:0
	s_add_u32 s8, s4, 0x2bc40
	s_addc_u32 s9, s5, 0x0
	global_load_lds_dwordx4 v238, s[8:9] offset:1024

; #define WAIT_V0() asm volatile("s_waitcnt vmcnt(0)" ::: "memory")
; #define SBAR() __builtin_amdgcn_sched_barrier(0)
; template <int EPI>
; DEVI void gemm_tile(const u16* __restrict__ Ab, long lda, const u16* __restrict__ Bb, long ldb, int K, const EpiArgs& e,
;                     bool have0 = false, const u16* __restrict__ nA = nullptr, const u16* __restrict__ nB = nullptr) {
;     ...
;   f32x4 acc[8][4];
; #pragma unroll
;   for (int m = 0; m < 8; ++m)
; #pragma unroll
;     for (int n = 0; n < 4; ++n) acc[m][n] = f32x4{0.f, 0.f, 0.f, 0.f};
;   const int nt = K / BK;
;   if (!have0) GLDS_STAGE(0, 0);
;   WAIT_V0(); __syncthreads();
;   for (int t = 0; t < nt; ++t) {
;     const int cur = t & 1;
;     if (t + 1 < nt) GLDS_STAGE(cur ^ 1, t + 1);
;     else if (nA) {
; #pragma unroll
;       for (int i = 0; i < GL; ++i) {
;         __builtin_amdgcn_global_load_lds((const unsigned*)(nA + (long)i * 64 * lda + toffA), (unsigned*)(g_shm + wid * 1024 + i * 8192), 16, 0, 0);
;         __builtin_amdgcn_global_load_lds((const unsigned*)(nB + (long)i * 64 * ldb + toffB), (unsigned*)(g_shm + TILE_B + wid * 1024 + i * 8192), 16, 0, 0);
;       }
;     }
;     const char* sb = g_shm + cur * STAGE_B;
; #pragma unroll
;     for (int ks = 0; ks < 2; ++ks) {
;       bf16x8 Bf[4];
; #pragma unroll
;       for (int n = 0; n < 4; ++n) Bf[n] = *(const bf16x8*)(sb + b_base + n * 2048 + ks * 1024);
; #pragma unroll
;       for (int mh = 0; mh < 2; ++mh) {
;         bf16x8 At[4];
; #pragma unroll
;         for (int m = 0; m < 4; ++m) At[m] = *(const bf16x8*)(sb + a_base + (mh * 4 + m) * 2048 + ks * 1024);
;         __builtin_amdgcn_s_setprio(1);
; #pragma unroll
;         for (int m = 0; m < 4; ++m)
; #pragma unroll
;           for (int n = 0; n < 4; ++n) acc[mh * 4 + m][n] = __builtin_amdgcn_mfma_f32_16x16x32_bf16(Bf[n], At[m], acc[mh * 4 + m][n], 0, 0, 0);
;         __builtin_amdgcn_s_setprio(0);
;       }
;       SBAR();
;     }
;     if (t + 1 < nt) { WAIT_V0(); __syncthreads(); }
;   }
.LBB0_359:
	s_and_b32 s3, s2, 0x10000
	v_or_b32_e32 v150, s3, v149
	v_add_u32_e32 v169, v150, v148
	v_or_b32_e32 v150, s3, v146
	v_add_u32_e32 v178, v150, v147
	ds_read_b128 v[150:153], v169 offset:32768
	ds_read_b128 v[154:157], v169 offset:34816
	ds_read_b128 v[158:161], v169 offset:36864
	ds_read_b128 v[162:165], v169 offset:38912
	ds_read_b128 v[170:173], v178
	ds_read_b128 v[174:177], v178 offset:2048
	ds_read_b128 v[192:195], v178 offset:4096
	ds_read_b128 v[198:201], v178 offset:6144
	v_writelane_b32 v240, s4, 0
	v_writelane_b32 v240, s5, 1
	v_writelane_b32 v240, s6, 2
	v_writelane_b32 v240, s7, 3
	v_writelane_b32 v240, s8, 4
	v_writelane_b32 v240, s9, 5
	v_writelane_b32 v240, s10, 6
	v_readfirstlane_b32 s4, v132
	v_readfirstlane_b32 s5, v133
	s_nop 1
	v_subrev_u32_e32 v238, s4, v132
	s_add_u32 s4, s4, s16
	s_addc_u32 s5, s5, s17
	v_readfirstlane_b32 s6, v134
	v_readfirstlane_b32 s7, v135
	s_nop 1
	v_subrev_u32_e32 v239, s6, v134
	s_add_u32 s6, s6, s16
	s_addc_u32 s7, s7, s17
	s_add_u32 s4, s4, 0x32500080
	s_addc_u32 s5, s5, 0
	s_add_u32 s6, s6, 0x99c0080
	s_addc_u32 s7, s7, 0
	v_readfirstlane_b32 s8, v142
	s_nop 3
	s_lshr_b32 s8, s8, 10
	s_mul_i32 s9, s8, 4
	s_mul_i32 s10, s8, 0
	s_add_i32 s10, s10, 16
	s_cmp_ge_u32 s8, 4
	s_cselect_b32 s10, s10, s9
	s_lshr_b32 s9, s8, 1
	s_sub_i32 s10, s10, s9
	s_lshl_b32 s10, s10, 4
	s_mul_hi_i32 s9, s10, 0x1000
	s_mul_i32 s10, s10, 0x1000
	s_and_b32 s8, s8, 1
	s_lshl_b32 s8, s8, 6
	s_sub_u32 s10, s10, s8
	s_subb_u32 s9, s9, 0
	s_add_u32 s4, s4, s10
	s_addc_u32 s5, s5, s9
	s_add_u32 s6, s6, s10
	s_addc_u32 s7, s7, s9
	s_cmp_eq_u32 s101, 0
	s_cbranch_scc0 .Lkl_359_s1
	v_readfirstlane_b32 s10, v142
	s_nop 3
	s_mul_i32 s8, s10, 8
	s_mul_i32 s9, s10, 0
	s_add_i32 s9, s9, 0x8000
	s_cmp_ge_u32 s10, 0x1000
	s_cselect_b32 s10, s9, s8
	s_xor_b32 s8, s3, 0x10000
	s_add_i32 s10, s10, s8
	s_add_i32 m0, s10, 0x1000
	s_add_u32 s8, s4, 0x1000
	s_addc_u32 s9, s5, 0x0
	global_load_lds_dwordx4 v238, s[8:9] offset:-4096
	s_add_u32 s8, s4, 0xc40
	s_addc_u32 s9, s5, 0x0
	global_load_lds_dwordx4 v238, s[8:9] offset:-3072
.Lkl_359_s1:
	s_cmp_eq_u32 s101, 0
	s_cbranch_scc0 .Lkl_359_s2
	s_add_u32 s8, s4, 0x10800
	s_addc_u32 s9, s5, 0x0
	global_load_lds_dwordx4 v238, s[8:9] offset:-2048
	s_add_u32 s8, s4, 0x10440
	s_addc_u32 s9, s5, 0x0
	global_load_lds_dwordx4 v238, s[8:9] offset:-1024
.Lkl_359_s2:
	s_cmp_eq_u32 s101, 0
	s_cbranch_scc0 .Lkl_359_s3
	s_add_u32 s8, s4, 0x20000
	s_addc_u32 s9, s5, 0x0
	global_load_lds_dwordx4 v238, s[8:9] offset:0
	s_add_u32 s8, s4, 0x1fc40
	s_addc_u32 s9, s5, 0x0
	global_load_lds_dwordx4 v238, s[8:9] offset:1024
.Lkl_359_s3:
.Lkl_359:
	s_waitcnt lgkmcnt(3)
	v_mfma_f32_16x16x32_bf16 v[126:129], v[150:153], v[170:173], v[126:129]
	v_mfma_f32_16x16x32_bf16 v[122:125], v[154:157], v[170:173], v[122:125]
	v_mfma_f32_16x16x32_bf16 v[118:121], v[158:161], v[170:173], v[118:121]
	v_mfma_f32_16x16x32_bf16 v[114:117], v[162:165], v[170:173], v[114:117]
	ds_read_b128 v[170:173], v178 offset:8192
	ds_read_b128 v[222:225], v169 offset:33792
	s_cmp_eq_u32 s101, 0
	s_cbranch_scc0 .Lkl_359_s4
	s_add_u32 s8, s4, 0x2f800
	s_addc_u32 s9, s5, 0x0
	global_load_lds_dwordx4 v238, s[8:9] offset:2048
	s_add_u32 s8, s4, 0x2f440
	s_addc_u32 s9, s5, 0x0
	global_load_lds_dwordx4 v238, s[8:9] offset:3072

; #define WAIT_V0() asm volatile("s_waitcnt vmcnt(0)" ::: "memory")
; #define SBAR() __builtin_amdgcn_sched_barrier(0)
; template <int EPI>
; DEVI void gemm_tile(const u16* __restrict__ Ab, long lda, const u16* __restrict__ Bb, long ldb, int K, const EpiArgs& e,
;                     bool have0 = false, const u16* __restrict__ nA = nullptr, const u16* __restrict__ nB = nullptr) {
;     ...
;   f32x4 acc[8][4];
; #pragma unroll
;   for (int m = 0; m < 8; ++m)
; #pragma unroll
;     for (int n = 0; n < 4; ++n) acc[m][n] = f32x4{0.f, 0.f, 0.f, 0.f};
;   const int nt = K / BK;
;   if (!have0) GLDS_STAGE(0, 0);
;   WAIT_V0(); __syncthreads();
;   for (int t = 0; t < nt; ++t) {
;     const int cur = t & 1;
;     if (t + 1 < nt) GLDS_STAGE(cur ^ 1, t + 1);
;     else if (nA) {
; #pragma unroll
;       for (int i = 0; i < GL; ++i) {
;         __builtin_amdgcn_global_load_lds((const unsigned*)(nA + (long)i * 64 * lda + toffA), (unsigned*)(g_shm + wid * 1024 + i * 8192), 16, 0, 0);
;         __builtin_amdgcn_global_load_lds((const unsigned*)(nB + (long)i * 64 * ldb + toffB), (unsigned*)(g_shm + TILE_B + wid * 1024 + i * 8192), 16, 0, 0);
;       }
;     }
;     const char* sb = g_shm + cur * STAGE_B;
; #pragma unroll
;     for (int ks = 0; ks < 2; ++ks) {
;       bf16x8 Bf[4];
; #pragma unroll
;       for (int n = 0; n < 4; ++n) Bf[n] = *(const bf16x8*)(sb + b_base + n * 2048 + ks * 1024);
; #pragma unroll
;       for (int mh = 0; mh < 2; ++mh) {
;         bf16x8 At[4];
; #pragma unroll
;         for (int m = 0; m < 4; ++m) At[m] = *(const bf16x8*)(sb + a_base + (mh * 4 + m) * 2048 + ks * 1024);
;         __builtin_amdgcn_s_setprio(1);
; #pragma unroll
;         for (int m = 0; m < 4; ++m)
; #pragma unroll
;           for (int n = 0; n < 4; ++n) acc[mh * 4 + m][n] = __builtin_amdgcn_mfma_f32_16x16x32_bf16(Bf[n], At[m], acc[mh * 4 + m][n], 0, 0, 0);
;         __builtin_amdgcn_s_setprio(0);
;       }
;       SBAR();
;     }
;     if (t + 1 < nt) { WAIT_V0(); __syncthreads(); }
;   }
.Lkl_359_s5:
	s_waitcnt lgkmcnt(5)
	v_mfma_f32_16x16x32_bf16 v[94:97], v[150:153], v[192:195], v[94:97]
	v_mfma_f32_16x16x32_bf16 v[90:93], v[154:157], v[192:195], v[90:93]
	v_mfma_f32_16x16x32_bf16 v[86:89], v[158:161], v[192:195], v[86:89]
	v_mfma_f32_16x16x32_bf16 v[82:85], v[162:165], v[192:195], v[82:85]
	ds_read_b128 v[192:195], v178 offset:12288
	ds_read_b128 v[230:233], v169 offset:37888
	s_cmp_eq_u32 s101, 0
	s_cbranch_scc0 .Lkl_359_s6
	s_add_u32 s8, s6, 0x10800
	s_addc_u32 s9, s7, 0x0
	global_load_lds_dwordx4 v239, s[8:9] offset:-2048
	s_add_u32 s8, s6, 0x10440
	s_addc_u32 s9, s7, 0x0
	global_load_lds_dwordx4 v239, s[8:9] offset:-1024
.Lkl_359_s6:
	s_waitcnt lgkmcnt(6)
	v_mfma_f32_16x16x32_bf16 v[78:81], v[150:153], v[198:201], v[78:81]
	v_mfma_f32_16x16x32_bf16 v[74:77], v[154:157], v[198:201], v[74:77]
	v_mfma_f32_16x16x32_bf16 v[70:73], v[158:161], v[198:201], v[70:73]
	v_mfma_f32_16x16x32_bf16 v[66:69], v[162:165], v[198:201], v[66:69]
	ds_read_b128 v[198:201], v178 offset:14336
	ds_read_b128 v[234:237], v169 offset:39936
	s_cmp_eq_u32 s101, 0
	s_cbranch_scc0 .Lkl_359_s7
	s_add_u32 s8, s6, 0x20000
	s_addc_u32 s9, s7, 0x0
	global_load_lds_dwordx4 v239, s[8:9] offset:0
	s_add_u32 s8, s6, 0x1fc40
	s_addc_u32 s9, s7, 0x0
	global_load_lds_dwordx4 v239, s[8:9] offset:1024
.Lkl_359_s7:
	s_waitcnt lgkmcnt(7)
	v_mfma_f32_16x16x32_bf16 v[62:65], v[150:153], v[170:173], v[62:65]
	v_mfma_f32_16x16x32_bf16 v[58:61], v[154:157], v[170:173], v[58:61]
	v_mfma_f32_16x16x32_bf16 v[54:57], v[158:161], v[170:173], v[54:57]
	v_mfma_f32_16x16x32_bf16 v[50:53], v[162:165], v[170:173], v[50:53]
	ds_read_b128 v[170:173], v178 offset:1024
	s_cmp_eq_u32 s101, 0
	s_cbranch_scc0 .Lkl_359_s8
	s_add_u32 s8, s6, 0x2f800
	s_addc_u32 s9, s7, 0x0
	global_load_lds_dwordx4 v239, s[8:9] offset:2048
	s_add_u32 s8, s6, 0x2f440
	s_addc_u32 s9, s7, 0x0
	global_load_lds_dwordx4 v239, s[8:9] offset:3072
; #define WAIT_V0() asm volatile("s_waitcnt vmcnt(0)" ::: "memory")
; #define SBAR() __builtin_amdgcn_sched_barrier(0)
; template <int EPI>
; DEVI void gemm_tile(const u16* __restrict__ Ab, long lda, const u16* __restrict__ Bb, long ldb, int K, const EpiArgs& e,
;                     bool have0 = false, const u16* __restrict__ nA = nullptr, const u16* __restrict__ nB = nullptr) {
;     ...
;   for (int t = 0; t < nt; ++t) {
;     const int cur = t & 1;
;     if (t + 1 < nt) GLDS_STAGE(cur ^ 1, t + 1);
;     else if (nA) {
; #pragma unroll
;       for (int i = 0; i < GL; ++i) {
;         __builtin_amdgcn_global_load_lds((const unsigned*)(nA + (long)i * 64 * lda + toffA), (unsigned*)(g_shm + wid * 1024 + i * 8192), 16, 0, 0);
;         __builtin_amdgcn_global_load_lds((const unsigned*)(nB + (long)i * 64 * ldb + toffB), (unsigned*)(g_shm + TILE_B + wid * 1024 + i * 8192), 16, 0, 0);
;       }
;     }
;     const char* sb = g_shm + cur * STAGE_B;
; #pragma unroll
;     for (int ks = 0; ks < 2; ++ks) {
;       bf16x8 Bf[4];
; #pragma unroll
;       for (int n = 0; n < 4; ++n) Bf[n] = *(const bf16x8*)(sb + b_base + n * 2048 + ks * 1024);
; #pragma unroll
;       for (int mh = 0; mh < 2; ++mh) {
;         bf16x8 At[4];
; #pragma unroll
;         for (int m = 0; m < 4; ++m) At[m] = *(const bf16x8*)(sb + a_base + (mh * 4 + m) * 2048 + ks * 1024);
;         __builtin_amdgcn_s_setprio(1);
; #pragma unroll
;         for (int m = 0; m < 4; ++m)
; #pragma unroll
;           for (int n = 0; n < 4; ++n) acc[mh * 4 + m][n] = __builtin_amdgcn_mfma_f32_16x16x32_bf16(Bf[n], At[m], acc[mh * 4 + m][n], 0, 0, 0);
;         __builtin_amdgcn_s_setprio(0);
;       }
;       SBAR();
;     }
;     if (t + 1 < nt) { WAIT_V0(); __syncthreads(); }
;   }
.Lkl_359_s8:
	s_waitcnt lgkmcnt(6)
	v_mfma_f32_16x16x32_bf16 v[46:49], v[150:153], v[174:177], v[46:49]
	v_mfma_f32_16x16x32_bf16 v[42:45], v[154:157], v[174:177], v[42:45]
	v_mfma_f32_16x16x32_bf16 v[38:41], v[158:161], v[174:177], v[38:41]
	v_mfma_f32_16x16x32_bf16 v[34:37], v[162:165], v[174:177], v[34:37]
	ds_read_b128 v[174:177], v178 offset:3072
	s_waitcnt lgkmcnt(5)
	v_mfma_f32_16x16x32_bf16 v[30:33], v[150:153], v[192:195], v[30:33]
	v_mfma_f32_16x16x32_bf16 v[26:29], v[154:157], v[192:195], v[26:29]
	v_mfma_f32_16x16x32_bf16 v[22:25], v[158:161], v[192:195], v[22:25]
	v_mfma_f32_16x16x32_bf16 v[18:21], v[162:165], v[192:195], v[18:21]
	ds_read_b128 v[192:195], v178 offset:5120
	s_waitcnt lgkmcnt(4)
	v_mfma_f32_16x16x32_bf16 v[14:17], v[150:153], v[198:201], v[14:17]
	v_mfma_f32_16x16x32_bf16 v[10:13], v[154:157], v[198:201], v[10:13]
	v_mfma_f32_16x16x32_bf16 v[6:9], v[158:161], v[198:201], v[6:9]
	v_mfma_f32_16x16x32_bf16 v[2:5], v[162:165], v[198:201], v[2:5]
	ds_read_b128 v[198:201], v178 offset:7168
	s_waitcnt lgkmcnt(3)
	v_mfma_f32_16x16x32_bf16 v[126:129], v[222:225], v[170:173], v[126:129]
	v_mfma_f32_16x16x32_bf16 v[122:125], v[226:229], v[170:173], v[122:125]
	v_mfma_f32_16x16x32_bf16 v[118:121], v[230:233], v[170:173], v[118:121]
	v_mfma_f32_16x16x32_bf16 v[114:117], v[234:237], v[170:173], v[114:117]
	ds_read_b128 v[170:173], v178 offset:9216
	s_waitcnt lgkmcnt(3)
	v_mfma_f32_16x16x32_bf16 v[110:113], v[222:225], v[174:177], v[110:113]
	v_mfma_f32_16x16x32_bf16 v[106:109], v[226:229], v[174:177], v[106:109]
	v_mfma_f32_16x16x32_bf16 v[102:105], v[230:233], v[174:177], v[102:105]
	v_mfma_f32_16x16x32_bf16 v[98:101], v[234:237], v[174:177], v[98:101]
	ds_read_b128 v[174:177], v178 offset:11264
	s_waitcnt lgkmcnt(3)
	v_mfma_f32_16x16x32_bf16 v[94:97], v[222:225], v[192:195], v[94:97]
	v_mfma_f32_16x16x32_bf16 v[90:93], v[226:229], v[192:195], v[90:93]
	v_mfma_f32_16x16x32_bf16 v[86:89], v[230:233], v[192:195], v[86:89]
	v_mfma_f32_16x16x32_bf16 v[82:85], v[234:237], v[192:195], v[82:85]
	ds_read_b128 v[192:195], v178 offset:13312
	s_waitcnt lgkmcnt(3)
	v_mfma_f32_16x16x32_bf16 v[78:81], v[222:225], v[198:201], v[78:81]
	v_mfma_f32_16x16x32_bf16 v[74:77], v[226:229], v[198:201], v[74:77]
	v_mfma_f32_16x16x32_bf16 v[70:73], v[230:233], v[198:201], v[70:73]
	v_mfma_f32_16x16x32_bf16 v[66:69], v[234:237], v[198:201], v[66:69]
	ds_read_b128 v[198:201], v178 offset:15360
	s_waitcnt lgkmcnt(3)
	v_mfma_f32_16x16x32_bf16 v[62:65], v[222:225], v[170:173], v[62:65]
	v_mfma_f32_16x16x32_bf16 v[58:61], v[226:229], v[170:173], v[58:61]
	v_mfma_f32_16x16x32_bf16 v[54:57], v[230:233], v[170:173], v[54:57]
	v_mfma_f32_16x16x32_bf16 v[50:53], v[234:237], v[170:173], v[50:53]
	s_waitcnt lgkmcnt(2)
	v_mfma_f32_16x16x32_bf16 v[46:49], v[222:225], v[174:177], v[46:49]
	v_mfma_f32_16x16x32_bf16 v[42:45], v[226:229], v[174:177], v[42:45]
	v_mfma_f32_16x16x32_bf16 v[38:41], v[230:233], v[174:177], v[38:41]
	v_mfma_f32_16x16x32_bf16 v[34:37], v[234:237], v[174:177], v[34:37]
	s_waitcnt lgkmcnt(0)
	s_waitcnt vmcnt(0)
	s_add_u32 s16, s16, 0x80
	s_addc_u32 s17, s17, 0
	s_add_i32 s2, s2, 0x10000
	s_cmpk_eq_i32 s16, 0xf80
	s_waitcnt vmcnt(0)
	s_barrier
	s_cselect_b32 s100, 1, 0
	s_and_b32 s3, s2, 0x10000
	v_or_b32_e32 v150, s3, v149
	v_add_u32_e32 v169, v150, v148
	v_or_b32_e32 v150, s3, v146
	v_add_u32_e32 v178, v150, v147
	ds_read_b128 v[150:153], v169 offset:32768
	ds_read_b128 v[154:157], v169 offset:34816
	ds_read_b128 v[158:161], v169 offset:36864
	ds_read_b128 v[162:165], v169 offset:38912
	ds_read_b128 v[170:173], v178
	ds_read_b128 v[174:177], v178 offset:2048
	s_add_u32 s4, s4, 0x80
	s_addc_u32 s5, s5, 0
	s_add_u32 s6, s6, 0x80
	s_addc_u32 s7, s7, 0
	s_cmp_eq_u32 s100, 1
	s_cbranch_scc1 .Lkl_359_s9
	s_cmp_eq_u32 s101, 0
	s_cbranch_scc0 .Lkl_359_s9
	v_readfirstlane_b32 s10, v142
	s_nop 3
	s_mul_i32 s8, s10, 8
	s_mul_i32 s9, s10, 0
	s_add_i32 s9, s9, 0x8000
	s_cmp_ge_u32 s10, 0x1000
	s_cselect_b32 s10, s9, s8
	s_xor_b32 s8, s3, 0x10000
	s_add_i32 s10, s10, s8
	s_add_i32 m0, s10, 0x1000
	s_add_u32 s8, s4, 0x1000
	s_addc_u32 s9, s5, 0x0
	global_load_lds_dwordx4 v238, s[8:9] offset:-4096
	s_add_u32 s8, s4, 0xc40
	s_addc_u32 s9, s5, 0x0
	global_load_lds_dwordx4 v238, s[8:9] offset:-3072
.Lkl_359_s9:
	v_mfma_f32_16x16x32_bf16 v[30:33], v[222:225], v[192:195], v[30:33]
	v_mfma_f32_16x16x32_bf16 v[26:29], v[226:229], v[192:195], v[26:29]
	v_mfma_f32_16x16x32_bf16 v[22:25], v[230:233], v[192:195], v[22:25]
	v_mfma_f32_16x16x32_bf16 v[18:21], v[234:237], v[192:195], v[18:21]
	ds_read_b128 v[192:195], v178 offset:4096
	s_cmp_eq_u32 s100, 1
	s_cbranch_scc1 .Lkl_359_s10
	s_cmp_eq_u32 s101, 0
	s_cbranch_scc0 .Lkl_359_s10
	s_add_u32 s8, s4, 0x10800
	s_addc_u32 s9, s5, 0x0
	global_load_lds_dwordx4 v238, s[8:9] offset:-2048
	s_add_u32 s8, s4, 0x10440
	s_addc_u32 s9, s5, 0x0
	global_load_lds_dwordx4 v238, s[8:9] offset:-1024
.Lkl_359_s10:
	v_mfma_f32_16x16x32_bf16 v[14:17], v[222:225], v[198:201], v[14:17]
	v_mfma_f32_16x16x32_bf16 v[10:13], v[226:229], v[198:201], v[10:13]
	v_mfma_f32_16x16x32_bf16 v[6:9], v[230:233], v[198:201], v[6:9]
	v_mfma_f32_16x16x32_bf16 v[2:5], v[234:237], v[198:201], v[2:5]
	ds_read_b128 v[198:201], v178 offset:6144
	s_cmp_eq_u32 s100, 1
	s_cbranch_scc1 .Lkl_359_s11
	s_cmp_eq_u32 s101, 0
	s_cbranch_scc0 .Lkl_359_s11
	s_add_u32 s8, s4, 0x20000
	s_addc_u32 s9, s5, 0x0
	global_load_lds_dwordx4 v238, s[8:9] offset:0
	s_add_u32 s8, s4, 0x1fc40
	s_addc_u32 s9, s5, 0x0
	global_load_lds_dwordx4 v238, s[8:9] offset:1024

; #define WAIT_V0() asm volatile("s_waitcnt vmcnt(0)" ::: "memory")
; #define SBAR() __builtin_amdgcn_sched_barrier(0)
; template <int EPI>
; DEVI void gemm_tile(const u16* __restrict__ Ab, long lda, const u16* __restrict__ Bb, long ldb, int K, const EpiArgs& e,
;                     bool have0 = false, const u16* __restrict__ nA = nullptr, const u16* __restrict__ nB = nullptr) {
;     ...
;   f32x4 acc[8][4];
; #pragma unroll
;   for (int m = 0; m < 8; ++m)
; #pragma unroll
;     for (int n = 0; n < 4; ++n) acc[m][n] = f32x4{0.f, 0.f, 0.f, 0.f};
;   const int nt = K / BK;
;   if (!have0) GLDS_STAGE(0, 0);
;   WAIT_V0(); __syncthreads();
;   for (int t = 0; t < nt; ++t) {
;     const int cur = t & 1;
;     if (t + 1 < nt) GLDS_STAGE(cur ^ 1, t + 1);
;     else if (nA) {
; #pragma unroll
;       for (int i = 0; i < GL; ++i) {
;         __builtin_amdgcn_global_load_lds((const unsigned*)(nA + (long)i * 64 * lda + toffA), (unsigned*)(g_shm + wid * 1024 + i * 8192), 16, 0, 0);
;         __builtin_amdgcn_global_load_lds((const unsigned*)(nB + (long)i * 64 * ldb + toffB), (unsigned*)(g_shm + TILE_B + wid * 1024 + i * 8192), 16, 0, 0);
;       }
;     }
;     const char* sb = g_shm + cur * STAGE_B;
; #pragma unroll
;     for (int ks = 0; ks < 2; ++ks) {
;       bf16x8 Bf[4];
; #pragma unroll
;       for (int n = 0; n < 4; ++n) Bf[n] = *(const bf16x8*)(sb + b_base + n * 2048 + ks * 1024);
; #pragma unroll
;       for (int mh = 0; mh < 2; ++mh) {
;         bf16x8 At[4];
; #pragma unroll
;         for (int m = 0; m < 4; ++m) At[m] = *(const bf16x8*)(sb + a_base + (mh * 4 + m) * 2048 + ks * 1024);
;         __builtin_amdgcn_s_setprio(1);
; #pragma unroll
;         for (int m = 0; m < 4; ++m)
; #pragma unroll
;           for (int n = 0; n < 4; ++n) acc[mh * 4 + m][n] = __builtin_amdgcn_mfma_f32_16x16x32_bf16(Bf[n], At[m], acc[mh * 4 + m][n], 0, 0, 0);
;         __builtin_amdgcn_s_setprio(0);
;       }
;       SBAR();
;     }
;     if (t + 1 < nt) { WAIT_V0(); __syncthreads(); }
;   }
.LBB0_459:
	s_and_b32 s3, s2, 0x10000
	v_or_b32_e32 v150, s3, v149
	v_add_u32_e32 v169, v150, v148
	v_or_b32_e32 v150, s3, v146
	v_add_u32_e32 v178, v150, v147
	ds_read_b128 v[150:153], v169 offset:32768
	ds_read_b128 v[154:157], v169 offset:34816
	ds_read_b128 v[158:161], v169 offset:36864
	ds_read_b128 v[162:165], v169 offset:38912
	ds_read_b128 v[170:173], v178
	ds_read_b128 v[174:177], v178 offset:2048
	ds_read_b128 v[192:195], v178 offset:4096
	ds_read_b128 v[198:201], v178 offset:6144
	v_writelane_b32 v240, s4, 0
	v_writelane_b32 v240, s5, 1
	v_writelane_b32 v240, s6, 2
	v_writelane_b32 v240, s7, 3
	v_writelane_b32 v240, s8, 4
	v_writelane_b32 v240, s9, 5
	v_writelane_b32 v240, s10, 6
	v_readfirstlane_b32 s4, v132
	v_readfirstlane_b32 s5, v133
	s_nop 1
	v_subrev_u32_e32 v238, s4, v132
	s_add_u32 s4, s4, s14
	s_addc_u32 s5, s5, s15
	v_readfirstlane_b32 s6, v134
	v_readfirstlane_b32 s7, v135
	s_nop 1
	v_subrev_u32_e32 v239, s6, v134
	s_add_u32 s6, s6, s14
	s_addc_u32 s7, s7, s15
	s_add_u32 s4, s4, s30
	s_addc_u32 s5, s5, s31
	s_add_u32 s6, s6, s20
	s_addc_u32 s7, s7, s21
	v_readfirstlane_b32 s8, v142
	s_nop 3
	s_lshr_b32 s8, s8, 10
	s_mul_i32 s9, s8, 4
	s_mul_i32 s10, s8, 0
	s_add_i32 s10, s10, 16
	s_cmp_ge_u32 s8, 4
	s_cselect_b32 s10, s10, s9
	s_lshr_b32 s9, s8, 1
	s_sub_i32 s10, s10, s9
	s_lshl_b32 s10, s10, 4
	s_mul_hi_i32 s9, s10, 0x800
	s_mul_i32 s10, s10, 0x800
	s_and_b32 s8, s8, 1
	s_lshl_b32 s8, s8, 6
	s_sub_u32 s10, s10, s8
	s_subb_u32 s9, s9, 0
	s_add_u32 s4, s4, s10
	s_addc_u32 s5, s5, s9
	s_add_u32 s6, s6, s10
	s_addc_u32 s7, s7, s9
	s_cmp_eq_u32 s101, 0
	s_cbranch_scc0 .Lkl_459_s1
	v_readfirstlane_b32 s10, v142
	s_nop 3
	s_mul_i32 s8, s10, 8
	s_mul_i32 s9, s10, 0
	s_add_i32 s9, s9, 0x8000
	s_cmp_ge_u32 s10, 0x1000
	s_cselect_b32 s10, s9, s8
	s_xor_b32 s8, s3, 0x10000
	s_add_i32 s10, s10, s8
	s_add_i32 m0, s10, 0x1000
	s_add_u32 s8, s4, 0x1000
	s_addc_u32 s9, s5, 0x0
	global_load_lds_dwordx4 v238, s[8:9] offset:-4096
	s_add_u32 s8, s4, 0xc40
	s_addc_u32 s9, s5, 0x0
	global_load_lds_dwordx4 v238, s[8:9] offset:-3072

; #define WAIT_V0() asm volatile("s_waitcnt vmcnt(0)" ::: "memory")
; #define SBAR() __builtin_amdgcn_sched_barrier(0)
; template <int EPI>
; DEVI void gemm_tile(const u16* __restrict__ Ab, long lda, const u16* __restrict__ Bb, long ldb, int K, const EpiArgs& e,
;                     bool have0 = false, const u16* __restrict__ nA = nullptr, const u16* __restrict__ nB = nullptr) {
;     ...
;   f32x4 acc[8][4];
; #pragma unroll
;   for (int m = 0; m < 8; ++m)
; #pragma unroll
;     for (int n = 0; n < 4; ++n) acc[m][n] = f32x4{0.f, 0.f, 0.f, 0.f};
;   const int nt = K / BK;
;   if (!have0) GLDS_STAGE(0, 0);
;   WAIT_V0(); __syncthreads();
;   for (int t = 0; t < nt; ++t) {
;     const int cur = t & 1;
;     if (t + 1 < nt) GLDS_STAGE(cur ^ 1, t + 1);
;     else if (nA) {
; #pragma unroll
;       for (int i = 0; i < GL; ++i) {
;         __builtin_amdgcn_global_load_lds((const unsigned*)(nA + (long)i * 64 * lda + toffA), (unsigned*)(g_shm + wid * 1024 + i * 8192), 16, 0, 0);
;         __builtin_amdgcn_global_load_lds((const unsigned*)(nB + (long)i * 64 * ldb + toffB), (unsigned*)(g_shm + TILE_B + wid * 1024 + i * 8192), 16, 0, 0);
;       }
;     }
;     const char* sb = g_shm + cur * STAGE_B;
; #pragma unroll
;     for (int ks = 0; ks < 2; ++ks) {
;       bf16x8 Bf[4];
; #pragma unroll
;       for (int n = 0; n < 4; ++n) Bf[n] = *(const bf16x8*)(sb + b_base + n * 2048 + ks * 1024);
; #pragma unroll
;       for (int mh = 0; mh < 2; ++mh) {
;         bf16x8 At[4];
; #pragma unroll
;         for (int m = 0; m < 4; ++m) At[m] = *(const bf16x8*)(sb + a_base + (mh * 4 + m) * 2048 + ks * 1024);
;         __builtin_amdgcn_s_setprio(1);
; #pragma unroll
;         for (int m = 0; m < 4; ++m)
; #pragma unroll
;           for (int n = 0; n < 4; ++n) acc[mh * 4 + m][n] = __builtin_amdgcn_mfma_f32_16x16x32_bf16(Bf[n], At[m], acc[mh * 4 + m][n], 0, 0, 0);
;         __builtin_amdgcn_s_setprio(0);
;       }
;       SBAR();
;     }
;     if (t + 1 < nt) { WAIT_V0(); __syncthreads(); }
;   }
.Lkl_459_s3:
.Lkl_459:
	s_waitcnt lgkmcnt(3)
	v_mfma_f32_16x16x32_bf16 v[126:129], v[150:153], v[170:173], v[126:129]
	v_mfma_f32_16x16x32_bf16 v[122:125], v[154:157], v[170:173], v[122:125]
	v_mfma_f32_16x16x32_bf16 v[118:121], v[158:161], v[170:173], v[118:121]
	v_mfma_f32_16x16x32_bf16 v[114:117], v[162:165], v[170:173], v[114:117]
	ds_read_b128 v[170:173], v178 offset:8192
	ds_read_b128 v[222:225], v169 offset:33792
	s_cmp_eq_u32 s101, 0
	s_cbranch_scc0 .Lkl_459_s4
	s_add_u32 s8, s4, 0x17800
	s_addc_u32 s9, s5, 0x0
	global_load_lds_dwordx4 v238, s[8:9] offset:2048
	s_add_u32 s8, s4, 0x17440
	s_addc_u32 s9, s5, 0x0
	global_load_lds_dwordx4 v238, s[8:9] offset:3072

; #define WAIT_V0() asm volatile("s_waitcnt vmcnt(0)" ::: "memory")
; #define SBAR() __builtin_amdgcn_sched_barrier(0)
; template <int EPI>
; DEVI void gemm_tile(const u16* __restrict__ Ab, long lda, const u16* __restrict__ Bb, long ldb, int K, const EpiArgs& e,
;                     bool have0 = false, const u16* __restrict__ nA = nullptr, const u16* __restrict__ nB = nullptr) {
;     ...
;   f32x4 acc[8][4];
; #pragma unroll
;   for (int m = 0; m < 8; ++m)
; #pragma unroll
;     for (int n = 0; n < 4; ++n) acc[m][n] = f32x4{0.f, 0.f, 0.f, 0.f};
;   const int nt = K / BK;
;   if (!have0) GLDS_STAGE(0, 0);
;   WAIT_V0(); __syncthreads();
;   for (int t = 0; t < nt; ++t) {
;     const int cur = t & 1;
;     if (t + 1 < nt) GLDS_STAGE(cur ^ 1, t + 1);
;     else if (nA) {
; #pragma unroll
;       for (int i = 0; i < GL; ++i) {
;         __builtin_amdgcn_global_load_lds((const unsigned*)(nA + (long)i * 64 * lda + toffA), (unsigned*)(g_shm + wid * 1024 + i * 8192), 16, 0, 0);
;         __builtin_amdgcn_global_load_lds((const unsigned*)(nB + (long)i * 64 * ldb + toffB), (unsigned*)(g_shm + TILE_B + wid * 1024 + i * 8192), 16, 0, 0);
;       }
;     }
;     const char* sb = g_shm + cur * STAGE_B;
; #pragma unroll
;     for (int ks = 0; ks < 2; ++ks) {
;       bf16x8 Bf[4];
; #pragma unroll
;       for (int n = 0; n < 4; ++n) Bf[n] = *(const bf16x8*)(sb + b_base + n * 2048 + ks * 1024);
; #pragma unroll
;       for (int mh = 0; mh < 2; ++mh) {
;         bf16x8 At[4];
; #pragma unroll
;         for (int m = 0; m < 4; ++m) At[m] = *(const bf16x8*)(sb + a_base + (mh * 4 + m) * 2048 + ks * 1024);
;         __builtin_amdgcn_s_setprio(1);
; #pragma unroll
;         for (int m = 0; m < 4; ++m)
; #pragma unroll
;           for (int n = 0; n < 4; ++n) acc[mh * 4 + m][n] = __builtin_amdgcn_mfma_f32_16x16x32_bf16(Bf[n], At[m], acc[mh * 4 + m][n], 0, 0, 0);
;         __builtin_amdgcn_s_setprio(0);
;       }
;       SBAR();
;     }
;     if (t + 1 < nt) { WAIT_V0(); __syncthreads(); }
;   }
.Lkl_459_s5:
	s_waitcnt lgkmcnt(5)
	v_mfma_f32_16x16x32_bf16 v[94:97], v[150:153], v[192:195], v[94:97]
	v_mfma_f32_16x16x32_bf16 v[90:93], v[154:157], v[192:195], v[90:93]
	v_mfma_f32_16x16x32_bf16 v[86:89], v[158:161], v[192:195], v[86:89]
	v_mfma_f32_16x16x32_bf16 v[82:85], v[162:165], v[192:195], v[82:85]
	ds_read_b128 v[192:195], v178 offset:12288
	ds_read_b128 v[230:233], v169 offset:37888
	s_cmp_eq_u32 s101, 0
	s_cbranch_scc0 .Lkl_459_s6
	s_add_u32 s8, s6, 0x8800
	s_addc_u32 s9, s7, 0x0
	global_load_lds_dwordx4 v239, s[8:9] offset:-2048
	s_add_u32 s8, s6, 0x8440
	s_addc_u32 s9, s7, 0x0
	global_load_lds_dwordx4 v239, s[8:9] offset:-1024
.Lkl_459_s6:
	s_waitcnt lgkmcnt(6)
	v_mfma_f32_16x16x32_bf16 v[78:81], v[150:153], v[198:201], v[78:81]
	v_mfma_f32_16x16x32_bf16 v[74:77], v[154:157], v[198:201], v[74:77]
	v_mfma_f32_16x16x32_bf16 v[70:73], v[158:161], v[198:201], v[70:73]
	v_mfma_f32_16x16x32_bf16 v[66:69], v[162:165], v[198:201], v[66:69]
	ds_read_b128 v[198:201], v178 offset:14336
	ds_read_b128 v[234:237], v169 offset:39936
	s_cmp_eq_u32 s101, 0
	s_cbranch_scc0 .Lkl_459_s7
	s_add_u32 s8, s6, 0x10000
	s_addc_u32 s9, s7, 0x0
	global_load_lds_dwordx4 v239, s[8:9] offset:0
	s_add_u32 s8, s6, 0xfc40
	s_addc_u32 s9, s7, 0x0
	global_load_lds_dwordx4 v239, s[8:9] offset:1024
.Lkl_459_s7:
	s_waitcnt lgkmcnt(7)
	v_mfma_f32_16x16x32_bf16 v[62:65], v[150:153], v[170:173], v[62:65]
	v_mfma_f32_16x16x32_bf16 v[58:61], v[154:157], v[170:173], v[58:61]
	v_mfma_f32_16x16x32_bf16 v[54:57], v[158:161], v[170:173], v[54:57]
	v_mfma_f32_16x16x32_bf16 v[50:53], v[162:165], v[170:173], v[50:53]
	ds_read_b128 v[170:173], v178 offset:1024
	s_cmp_eq_u32 s101, 0
	s_cbranch_scc0 .Lkl_459_s8
	s_add_u32 s8, s6, 0x17800
	s_addc_u32 s9, s7, 0x0
	global_load_lds_dwordx4 v239, s[8:9] offset:2048
	s_add_u32 s8, s6, 0x17440
	s_addc_u32 s9, s7, 0x0
	global_load_lds_dwordx4 v239, s[8:9] offset:3072
; #define WAIT_V0() asm volatile("s_waitcnt vmcnt(0)" ::: "memory")
; #define SBAR() __builtin_amdgcn_sched_barrier(0)
; template <int EPI>
; DEVI void gemm_tile(const u16* __restrict__ Ab, long lda, const u16* __restrict__ Bb, long ldb, int K, const EpiArgs& e,
;                     bool have0 = false, const u16* __restrict__ nA = nullptr, const u16* __restrict__ nB = nullptr) {
;     ...
;   for (int t = 0; t < nt; ++t) {
;     const int cur = t & 1;
;     if (t + 1 < nt) GLDS_STAGE(cur ^ 1, t + 1);
;     else if (nA) {
; #pragma unroll
;       for (int i = 0; i < GL; ++i) {
;         __builtin_amdgcn_global_load_lds((const unsigned*)(nA + (long)i * 64 * lda + toffA), (unsigned*)(g_shm + wid * 1024 + i * 8192), 16, 0, 0);
;         __builtin_amdgcn_global_load_lds((const unsigned*)(nB + (long)i * 64 * ldb + toffB), (unsigned*)(g_shm + TILE_B + wid * 1024 + i * 8192), 16, 0, 0);
;       }
;     }
;     const char* sb = g_shm + cur * STAGE_B;
; #pragma unroll
;     for (int ks = 0; ks < 2; ++ks) {
;       bf16x8 Bf[4];
; #pragma unroll
;       for (int n = 0; n < 4; ++n) Bf[n] = *(const bf16x8*)(sb + b_base + n * 2048 + ks * 1024);
; #pragma unroll
;       for (int mh = 0; mh < 2; ++mh) {
;         bf16x8 At[4];
; #pragma unroll
;         for (int m = 0; m < 4; ++m) At[m] = *(const bf16x8*)(sb + a_base + (mh * 4 + m) * 2048 + ks * 1024);
;         __builtin_amdgcn_s_setprio(1);
; #pragma unroll
;         for (int m = 0; m < 4; ++m)
; #pragma unroll
;           for (int n = 0; n < 4; ++n) acc[mh * 4 + m][n] = __builtin_amdgcn_mfma_f32_16x16x32_bf16(Bf[n], At[m], acc[mh * 4 + m][n], 0, 0, 0);
;         __builtin_amdgcn_s_setprio(0);
;       }
;       SBAR();
;     }
;     if (t + 1 < nt) { WAIT_V0(); __syncthreads(); }
;   }
.Lkl_459_s8:
	s_waitcnt lgkmcnt(6)
	v_mfma_f32_16x16x32_bf16 v[46:49], v[150:153], v[174:177], v[46:49]
	v_mfma_f32_16x16x32_bf16 v[42:45], v[154:157], v[174:177], v[42:45]
	v_mfma_f32_16x16x32_bf16 v[38:41], v[158:161], v[174:177], v[38:41]
	v_mfma_f32_16x16x32_bf16 v[34:37], v[162:165], v[174:177], v[34:37]
	ds_read_b128 v[174:177], v178 offset:3072
	s_waitcnt lgkmcnt(5)
	v_mfma_f32_16x16x32_bf16 v[30:33], v[150:153], v[192:195], v[30:33]
	v_mfma_f32_16x16x32_bf16 v[26:29], v[154:157], v[192:195], v[26:29]
	v_mfma_f32_16x16x32_bf16 v[22:25], v[158:161], v[192:195], v[22:25]
	v_mfma_f32_16x16x32_bf16 v[18:21], v[162:165], v[192:195], v[18:21]
	ds_read_b128 v[192:195], v178 offset:5120
	s_waitcnt lgkmcnt(4)
	v_mfma_f32_16x16x32_bf16 v[14:17], v[150:153], v[198:201], v[14:17]
	v_mfma_f32_16x16x32_bf16 v[10:13], v[154:157], v[198:201], v[10:13]
	v_mfma_f32_16x16x32_bf16 v[6:9], v[158:161], v[198:201], v[6:9]
	v_mfma_f32_16x16x32_bf16 v[2:5], v[162:165], v[198:201], v[2:5]
	ds_read_b128 v[198:201], v178 offset:7168
	s_waitcnt lgkmcnt(3)
	v_mfma_f32_16x16x32_bf16 v[126:129], v[222:225], v[170:173], v[126:129]
	v_mfma_f32_16x16x32_bf16 v[122:125], v[226:229], v[170:173], v[122:125]
	v_mfma_f32_16x16x32_bf16 v[118:121], v[230:233], v[170:173], v[118:121]
	v_mfma_f32_16x16x32_bf16 v[114:117], v[234:237], v[170:173], v[114:117]
	ds_read_b128 v[170:173], v178 offset:9216
	s_waitcnt lgkmcnt(3)
	v_mfma_f32_16x16x32_bf16 v[110:113], v[222:225], v[174:177], v[110:113]
	v_mfma_f32_16x16x32_bf16 v[106:109], v[226:229], v[174:177], v[106:109]
	v_mfma_f32_16x16x32_bf16 v[102:105], v[230:233], v[174:177], v[102:105]
	v_mfma_f32_16x16x32_bf16 v[98:101], v[234:237], v[174:177], v[98:101]
	ds_read_b128 v[174:177], v178 offset:11264
	s_waitcnt lgkmcnt(3)
	v_mfma_f32_16x16x32_bf16 v[94:97], v[222:225], v[192:195], v[94:97]
	v_mfma_f32_16x16x32_bf16 v[90:93], v[226:229], v[192:195], v[90:93]
	v_mfma_f32_16x16x32_bf16 v[86:89], v[230:233], v[192:195], v[86:89]
	v_mfma_f32_16x16x32_bf16 v[82:85], v[234:237], v[192:195], v[82:85]
	ds_read_b128 v[192:195], v178 offset:13312
	s_waitcnt lgkmcnt(3)
	v_mfma_f32_16x16x32_bf16 v[78:81], v[222:225], v[198:201], v[78:81]
	v_mfma_f32_16x16x32_bf16 v[74:77], v[226:229], v[198:201], v[74:77]
	v_mfma_f32_16x16x32_bf16 v[70:73], v[230:233], v[198:201], v[70:73]
	v_mfma_f32_16x16x32_bf16 v[66:69], v[234:237], v[198:201], v[66:69]
	ds_read_b128 v[198:201], v178 offset:15360
	s_waitcnt lgkmcnt(3)
	v_mfma_f32_16x16x32_bf16 v[62:65], v[222:225], v[170:173], v[62:65]
	v_mfma_f32_16x16x32_bf16 v[58:61], v[226:229], v[170:173], v[58:61]
	v_mfma_f32_16x16x32_bf16 v[54:57], v[230:233], v[170:173], v[54:57]
	v_mfma_f32_16x16x32_bf16 v[50:53], v[234:237], v[170:173], v[50:53]
	s_waitcnt lgkmcnt(2)
	v_mfma_f32_16x16x32_bf16 v[46:49], v[222:225], v[174:177], v[46:49]
	v_mfma_f32_16x16x32_bf16 v[42:45], v[226:229], v[174:177], v[42:45]
	v_mfma_f32_16x16x32_bf16 v[38:41], v[230:233], v[174:177], v[38:41]
	v_mfma_f32_16x16x32_bf16 v[34:37], v[234:237], v[174:177], v[34:37]
	s_waitcnt lgkmcnt(0)
	s_waitcnt vmcnt(0)
	s_add_u32 s14, s14, 0x80
	s_addc_u32 s15, s15, 0
	s_add_i32 s2, s2, 0x10000
	s_cmpk_eq_i32 s14, 0x780
	s_waitcnt vmcnt(0)
	s_barrier
	s_cselect_b32 s100, 1, 0
	s_and_b32 s3, s2, 0x10000
	v_or_b32_e32 v150, s3, v149
	v_add_u32_e32 v169, v150, v148
	v_or_b32_e32 v150, s3, v146
	v_add_u32_e32 v178, v150, v147
	ds_read_b128 v[150:153], v169 offset:32768
	ds_read_b128 v[154:157], v169 offset:34816
	ds_read_b128 v[158:161], v169 offset:36864
	ds_read_b128 v[162:165], v169 offset:38912
	ds_read_b128 v[170:173], v178
	ds_read_b128 v[174:177], v178 offset:2048
	s_add_u32 s4, s4, 0x80
	s_addc_u32 s5, s5, 0
	s_add_u32 s6, s6, 0x80
	s_addc_u32 s7, s7, 0
	s_cmp_eq_u32 s100, 1
	s_cbranch_scc1 .Lkl_459_s9
	s_cmp_eq_u32 s101, 0
	s_cbranch_scc0 .Lkl_459_s9
	v_readfirstlane_b32 s10, v142
	s_nop 3
	s_mul_i32 s8, s10, 8
	s_mul_i32 s9, s10, 0
	s_add_i32 s9, s9, 0x8000
	s_cmp_ge_u32 s10, 0x1000
	s_cselect_b32 s10, s9, s8
	s_xor_b32 s8, s3, 0x10000
	s_add_i32 s10, s10, s8
	s_add_i32 m0, s10, 0x1000
	s_add_u32 s8, s4, 0x1000
	s_addc_u32 s9, s5, 0x0
	global_load_lds_dwordx4 v238, s[8:9] offset:-4096
	s_add_u32 s8, s4, 0xc40
	s_addc_u32 s9, s5, 0x0
	global_load_lds_dwordx4 v238, s[8:9] offset:-3072
.Lkl_459_s9:
	v_mfma_f32_16x16x32_bf16 v[30:33], v[222:225], v[192:195], v[30:33]
	v_mfma_f32_16x16x32_bf16 v[26:29], v[226:229], v[192:195], v[26:29]
	v_mfma_f32_16x16x32_bf16 v[22:25], v[230:233], v[192:195], v[22:25]
	v_mfma_f32_16x16x32_bf16 v[18:21], v[234:237], v[192:195], v[18:21]
	ds_read_b128 v[192:195], v178 offset:4096
	s_cmp_eq_u32 s100, 1
	s_cbranch_scc1 .Lkl_459_s10
	s_cmp_eq_u32 s101, 0
	s_cbranch_scc0 .Lkl_459_s10
	s_add_u32 s8, s4, 0x8800
	s_addc_u32 s9, s5, 0x0
	global_load_lds_dwordx4 v238, s[8:9] offset:-2048
	s_add_u32 s8, s4, 0x8440
	s_addc_u32 s9, s5, 0x0
	global_load_lds_dwordx4 v238, s[8:9] offset:-1024
.Lkl_459_s10:
	v_mfma_f32_16x16x32_bf16 v[14:17], v[222:225], v[198:201], v[14:17]
	v_mfma_f32_16x16x32_bf16 v[10:13], v[226:229], v[198:201], v[10:13]
	v_mfma_f32_16x16x32_bf16 v[6:9], v[230:233], v[198:201], v[6:9]
	v_mfma_f32_16x16x32_bf16 v[2:5], v[234:237], v[198:201], v[2:5]
	ds_read_b128 v[198:201], v178 offset:6144
	s_cmp_eq_u32 s100, 1
	s_cbranch_scc1 .Lkl_459_s11
	s_cmp_eq_u32 s101, 0
	s_cbranch_scc0 .Lkl_459_s11
	s_add_u32 s8, s4, 0x10000
	s_addc_u32 s9, s5, 0x0
	global_load_lds_dwordx4 v238, s[8:9] offset:0
	s_add_u32 s8, s4, 0xfc40
	s_addc_u32 s9, s5, 0x0
	global_load_lds_dwordx4 v238, s[8:9] offset:1024

; #define WAIT_V0() asm volatile("s_waitcnt vmcnt(0)" ::: "memory")
; #define SBAR() __builtin_amdgcn_sched_barrier(0)
; template <int EPI>
; DEVI void gemm_tile(const u16* __restrict__ Ab, long lda, const u16* __restrict__ Bb, long ldb, int K, const EpiArgs& e,
;                     bool have0 = false, const u16* __restrict__ nA = nullptr, const u16* __restrict__ nB = nullptr) {
;     ...
;   f32x4 acc[8][4];
; #pragma unroll
;   for (int m = 0; m < 8; ++m)
; #pragma unroll
;     for (int n = 0; n < 4; ++n) acc[m][n] = f32x4{0.f, 0.f, 0.f, 0.f};
;   const int nt = K / BK;
;   if (!have0) GLDS_STAGE(0, 0);
;   WAIT_V0(); __syncthreads();
;   for (int t = 0; t < nt; ++t) {
;     const int cur = t & 1;
;     if (t + 1 < nt) GLDS_STAGE(cur ^ 1, t + 1);
;     else if (nA) {
; #pragma unroll
;       for (int i = 0; i < GL; ++i) {
;         __builtin_amdgcn_global_load_lds((const unsigned*)(nA + (long)i * 64 * lda + toffA), (unsigned*)(g_shm + wid * 1024 + i * 8192), 16, 0, 0);
;         __builtin_amdgcn_global_load_lds((const unsigned*)(nB + (long)i * 64 * ldb + toffB), (unsigned*)(g_shm + TILE_B + wid * 1024 + i * 8192), 16, 0, 0);
;       }
;     }
;     const char* sb = g_shm + cur * STAGE_B;
; #pragma unroll
;     for (int ks = 0; ks < 2; ++ks) {
;       bf16x8 Bf[4];
; #pragma unroll
;       for (int n = 0; n < 4; ++n) Bf[n] = *(const bf16x8*)(sb + b_base + n * 2048 + ks * 1024);
; #pragma unroll
;       for (int mh = 0; mh < 2; ++mh) {
;         bf16x8 At[4];
; #pragma unroll
;         for (int m = 0; m < 4; ++m) At[m] = *(const bf16x8*)(sb + a_base + (mh * 4 + m) * 2048 + ks * 1024);
;         __builtin_amdgcn_s_setprio(1);
; #pragma unroll
;         for (int m = 0; m < 4; ++m)
; #pragma unroll
;           for (int n = 0; n < 4; ++n) acc[mh * 4 + m][n] = __builtin_amdgcn_mfma_f32_16x16x32_bf16(Bf[n], At[m], acc[mh * 4 + m][n], 0, 0, 0);
;         __builtin_amdgcn_s_setprio(0);
;       }
;       SBAR();
;     }
;     if (t + 1 < nt) { WAIT_V0(); __syncthreads(); }
;   }
.LBB0_710:
	s_and_b32 s3, s2, 0x10000
	v_or_b32_e32 v150, s3, v149
	v_add_u32_e32 v169, v150, v148
	v_or_b32_e32 v150, s3, v146
	v_add_u32_e32 v178, v150, v147
	ds_read_b128 v[150:153], v169 offset:32768
	ds_read_b128 v[154:157], v169 offset:34816
	ds_read_b128 v[158:161], v169 offset:36864
	ds_read_b128 v[162:165], v169 offset:38912
	ds_read_b128 v[170:173], v178
	ds_read_b128 v[174:177], v178 offset:2048
	ds_read_b128 v[192:195], v178 offset:4096
	ds_read_b128 v[198:201], v178 offset:6144
	v_writelane_b32 v240, s4, 0
	v_writelane_b32 v240, s5, 1
	v_writelane_b32 v240, s6, 2
	v_writelane_b32 v240, s7, 3
	v_writelane_b32 v240, s8, 4
	v_writelane_b32 v240, s9, 5
	v_writelane_b32 v240, s10, 6
	v_readfirstlane_b32 s4, v132
	v_readfirstlane_b32 s5, v133
	s_nop 1
	v_subrev_u32_e32 v238, s4, v132
	s_add_u32 s4, s4, s14
	s_addc_u32 s5, s5, s15
	v_readfirstlane_b32 s6, v134
	v_readfirstlane_b32 s7, v135
	s_nop 1
	v_subrev_u32_e32 v239, s6, v134
	s_add_u32 s6, s6, s14
	s_addc_u32 s7, s7, s15
	s_add_u32 s4, s4, 0xe500080
	s_addc_u32 s5, s5, 0
	s_add_u32 s6, s6, s20
	s_addc_u32 s7, s7, s21
	v_readfirstlane_b32 s8, v142
	s_nop 3
	s_lshr_b32 s8, s8, 10
	s_mul_i32 s9, s8, 4
	s_mul_i32 s10, s8, 0
	s_add_i32 s10, s10, 16
	s_cmp_ge_u32 s8, 4
	s_cselect_b32 s10, s10, s9
	s_lshr_b32 s9, s8, 1
	s_sub_i32 s10, s10, s9
	s_lshl_b32 s10, s10, 4
	s_mul_hi_i32 s9, s10, 0x800
	s_mul_i32 s10, s10, 0x800
	s_and_b32 s8, s8, 1
	s_lshl_b32 s8, s8, 6
	s_sub_u32 s10, s10, s8
	s_subb_u32 s9, s9, 0
	s_add_u32 s4, s4, s10
	s_addc_u32 s5, s5, s9
	s_add_u32 s6, s6, s10
	s_addc_u32 s7, s7, s9
	s_cmp_eq_u32 s101, 0
	s_cbranch_scc0 .Lkl_710_s1
	v_readfirstlane_b32 s10, v142
	s_nop 3
	s_mul_i32 s8, s10, 8
	s_mul_i32 s9, s10, 0
	s_add_i32 s9, s9, 0x8000
	s_cmp_ge_u32 s10, 0x1000
	s_cselect_b32 s10, s9, s8
	s_xor_b32 s8, s3, 0x10000
	s_add_i32 s10, s10, s8
	s_add_i32 m0, s10, 0x1000
	s_add_u32 s8, s4, 0x1000
	s_addc_u32 s9, s5, 0x0
	global_load_lds_dwordx4 v238, s[8:9] offset:-4096
	s_add_u32 s8, s4, 0xc40
	s_addc_u32 s9, s5, 0x0
	global_load_lds_dwordx4 v238, s[8:9] offset:-3072

; #define WAIT_V0() asm volatile("s_waitcnt vmcnt(0)" ::: "memory")
; #define SBAR() __builtin_amdgcn_sched_barrier(0)
; template <int EPI>
; DEVI void gemm_tile(const u16* __restrict__ Ab, long lda, const u16* __restrict__ Bb, long ldb, int K, const EpiArgs& e,
;                     bool have0 = false, const u16* __restrict__ nA = nullptr, const u16* __restrict__ nB = nullptr) {
;     ...
;   f32x4 acc[8][4];
; #pragma unroll
;   for (int m = 0; m < 8; ++m)
; #pragma unroll
;     for (int n = 0; n < 4; ++n) acc[m][n] = f32x4{0.f, 0.f, 0.f, 0.f};
;   const int nt = K / BK;
;   if (!have0) GLDS_STAGE(0, 0);
;   WAIT_V0(); __syncthreads();
;   for (int t = 0; t < nt; ++t) {
;     const int cur = t & 1;
;     if (t + 1 < nt) GLDS_STAGE(cur ^ 1, t + 1);
;     else if (nA) {
; #pragma unroll
;       for (int i = 0; i < GL; ++i) {
;         __builtin_amdgcn_global_load_lds((const unsigned*)(nA + (long)i * 64 * lda + toffA), (unsigned*)(g_shm + wid * 1024 + i * 8192), 16, 0, 0);
;         __builtin_amdgcn_global_load_lds((const unsigned*)(nB + (long)i * 64 * ldb + toffB), (unsigned*)(g_shm + TILE_B + wid * 1024 + i * 8192), 16, 0, 0);
;       }
;     }
;     const char* sb = g_shm + cur * STAGE_B;
; #pragma unroll
;     for (int ks = 0; ks < 2; ++ks) {
;       bf16x8 Bf[4];
; #pragma unroll
;       for (int n = 0; n < 4; ++n) Bf[n] = *(const bf16x8*)(sb + b_base + n * 2048 + ks * 1024);
; #pragma unroll
;       for (int mh = 0; mh < 2; ++mh) {
;         bf16x8 At[4];
; #pragma unroll
;         for (int m = 0; m < 4; ++m) At[m] = *(const bf16x8*)(sb + a_base + (mh * 4 + m) * 2048 + ks * 1024);
;         __builtin_amdgcn_s_setprio(1);
; #pragma unroll
;         for (int m = 0; m < 4; ++m)
; #pragma unroll
;           for (int n = 0; n < 4; ++n) acc[mh * 4 + m][n] = __builtin_amdgcn_mfma_f32_16x16x32_bf16(Bf[n], At[m], acc[mh * 4 + m][n], 0, 0, 0);
;         __builtin_amdgcn_s_setprio(0);
;       }
;       SBAR();
;     }
;     if (t + 1 < nt) { WAIT_V0(); __syncthreads(); }
;   }
.LBB0_795:
	s_and_b32 s3, s2, 0x10000
	v_or_b32_e32 v150, s3, v149
	v_add_u32_e32 v169, v150, v148
	v_or_b32_e32 v150, s3, v146
	v_add_u32_e32 v178, v150, v147
	ds_read_b128 v[150:153], v169 offset:32768
	ds_read_b128 v[154:157], v169 offset:34816
	ds_read_b128 v[158:161], v169 offset:36864
	ds_read_b128 v[162:165], v169 offset:38912
	ds_read_b128 v[170:173], v178
	ds_read_b128 v[174:177], v178 offset:2048
	ds_read_b128 v[192:195], v178 offset:4096
	ds_read_b128 v[198:201], v178 offset:6144
	v_writelane_b32 v240, s4, 0
	v_writelane_b32 v240, s5, 1
	v_writelane_b32 v240, s6, 2
	v_writelane_b32 v240, s7, 3
	v_writelane_b32 v240, s8, 4
	v_writelane_b32 v240, s9, 5
	v_writelane_b32 v240, s10, 6
	v_readfirstlane_b32 s4, v132
	v_readfirstlane_b32 s5, v133
	s_nop 1
	v_subrev_u32_e32 v238, s4, v132
	s_add_u32 s4, s4, s14
	s_addc_u32 s5, s5, s15
	v_readfirstlane_b32 s6, v134
	v_readfirstlane_b32 s7, v135
	s_nop 1
	v_subrev_u32_e32 v239, s6, v134
	s_add_u32 s6, s6, s14
	s_addc_u32 s7, s7, s15
	s_add_u32 s4, s4, 0x12500080
	s_addc_u32 s5, s5, 0
	s_add_u32 s6, s6, s20
	s_addc_u32 s7, s7, s21
	v_readfirstlane_b32 s8, v142
	s_nop 3
	s_lshr_b32 s8, s8, 10
	s_mul_i32 s9, s8, 4
	s_mul_i32 s10, s8, 0
	s_add_i32 s10, s10, 16
	s_cmp_ge_u32 s8, 4
	s_cselect_b32 s10, s10, s9
	s_lshr_b32 s9, s8, 1
	s_sub_i32 s10, s10, s9
	s_lshl_b32 s10, s10, 4
	s_mul_hi_i32 s9, s10, 0x800
	s_mul_i32 s10, s10, 0x800
	s_and_b32 s8, s8, 1
	s_lshl_b32 s8, s8, 6
	s_sub_u32 s10, s10, s8
	s_subb_u32 s9, s9, 0
	s_add_u32 s4, s4, s10
	s_addc_u32 s5, s5, s9
	s_add_u32 s6, s6, s10
	s_addc_u32 s7, s7, s9
	s_cmp_eq_u32 s101, 0
	s_cbranch_scc0 .Lkl_795_s1
	v_readfirstlane_b32 s10, v142
	s_nop 3
	s_mul_i32 s8, s10, 8
	s_mul_i32 s9, s10, 0
	s_add_i32 s9, s9, 0x8000
	s_cmp_ge_u32 s10, 0x1000
	s_cselect_b32 s10, s9, s8
	s_xor_b32 s8, s3, 0x10000
	s_add_i32 s10, s10, s8
	s_add_i32 m0, s10, 0x1000
	s_add_u32 s8, s4, 0x1000
	s_addc_u32 s9, s5, 0x0
	global_load_lds_dwordx4 v238, s[8:9] offset:-4096
	s_add_u32 s8, s4, 0xc40
	s_addc_u32 s9, s5, 0x0
	global_load_lds_dwordx4 v238, s[8:9] offset:-3072

; #define WAIT_V0() asm volatile("s_waitcnt vmcnt(0)" ::: "memory")
; #define SBAR() __builtin_amdgcn_sched_barrier(0)
; template <int EPI>
; DEVI void gemm_tile(const u16* __restrict__ Ab, long lda, const u16* __restrict__ Bb, long ldb, int K, const EpiArgs& e,
;                     bool have0 = false, const u16* __restrict__ nA = nullptr, const u16* __restrict__ nB = nullptr) {
;     ...
;   f32x4 acc[8][4];
; #pragma unroll
;   for (int m = 0; m < 8; ++m)
; #pragma unroll
;     for (int n = 0; n < 4; ++n) acc[m][n] = f32x4{0.f, 0.f, 0.f, 0.f};
;   const int nt = K / BK;
;   if (!have0) GLDS_STAGE(0, 0);
;   WAIT_V0(); __syncthreads();
;   for (int t = 0; t < nt; ++t) {
;     const int cur = t & 1;
;     if (t + 1 < nt) GLDS_STAGE(cur ^ 1, t + 1);
;     else if (nA) {
; #pragma unroll
;       for (int i = 0; i < GL; ++i) {
;         __builtin_amdgcn_global_load_lds((const unsigned*)(nA + (long)i * 64 * lda + toffA), (unsigned*)(g_shm + wid * 1024 + i * 8192), 16, 0, 0);
;         __builtin_amdgcn_global_load_lds((const unsigned*)(nB + (long)i * 64 * ldb + toffB), (unsigned*)(g_shm + TILE_B + wid * 1024 + i * 8192), 16, 0, 0);
;       }
;     }
;     const char* sb = g_shm + cur * STAGE_B;
; #pragma unroll
;     for (int ks = 0; ks < 2; ++ks) {
;       bf16x8 Bf[4];
; #pragma unroll
;       for (int n = 0; n < 4; ++n) Bf[n] = *(const bf16x8*)(sb + b_base + n * 2048 + ks * 1024);
; #pragma unroll
;       for (int mh = 0; mh < 2; ++mh) {
;         bf16x8 At[4];
; #pragma unroll
;         for (int m = 0; m < 4; ++m) At[m] = *(const bf16x8*)(sb + a_base + (mh * 4 + m) * 2048 + ks * 1024);
;         __builtin_amdgcn_s_setprio(1);
; #pragma unroll
;         for (int m = 0; m < 4; ++m)
; #pragma unroll
;           for (int n = 0; n < 4; ++n) acc[mh * 4 + m][n] = __builtin_amdgcn_mfma_f32_16x16x32_bf16(Bf[n], At[m], acc[mh * 4 + m][n], 0, 0, 0);
;         __builtin_amdgcn_s_setprio(0);
;       }
;       SBAR();
;     }
;     if (t + 1 < nt) { WAIT_V0(); __syncthreads(); }
;   }
.LBB0_1085:
	s_and_b32 s3, s2, 0x10000
	v_or_b32_e32 v150, s3, v149
	v_add_u32_e32 v169, v150, v148
	v_or_b32_e32 v150, s3, v146
	v_add_u32_e32 v178, v150, v147
	ds_read_b128 v[150:153], v169 offset:32768
	ds_read_b128 v[154:157], v169 offset:34816
	ds_read_b128 v[158:161], v169 offset:36864
	ds_read_b128 v[162:165], v169 offset:38912
	ds_read_b128 v[170:173], v178
	ds_read_b128 v[174:177], v178 offset:2048
	ds_read_b128 v[192:195], v178 offset:4096
	ds_read_b128 v[198:201], v178 offset:6144
	v_writelane_b32 v240, s4, 0
	v_writelane_b32 v240, s5, 1
	v_writelane_b32 v240, s6, 2
	v_writelane_b32 v240, s7, 3
	v_writelane_b32 v240, s8, 4
	v_writelane_b32 v240, s9, 5
	v_writelane_b32 v240, s10, 6
	v_readfirstlane_b32 s4, v134
	v_readfirstlane_b32 s5, v135
	s_nop 1
	v_subrev_u32_e32 v238, s4, v134
	s_add_u32 s4, s4, s16
	s_addc_u32 s5, s5, s17
	v_readfirstlane_b32 s6, v136
	v_readfirstlane_b32 s7, v137
	s_nop 1
	v_subrev_u32_e32 v239, s6, v136
	s_add_u32 s6, s6, s16
	s_addc_u32 s7, s7, s17
	s_add_u32 s4, s4, s22
	s_addc_u32 s5, s5, s23
	s_add_u32 s6, s6, 0x97c0080
	s_addc_u32 s7, s7, 0
	v_readfirstlane_b32 s8, v142
	s_nop 3
	s_lshr_b32 s8, s8, 10
	s_mul_i32 s9, s8, 4
	s_mul_i32 s10, s8, 0
	s_add_i32 s10, s10, 16
	s_cmp_ge_u32 s8, 4
	s_cselect_b32 s10, s10, s9
	s_lshr_b32 s9, s8, 1
	s_sub_i32 s10, s10, s9
	s_lshl_b32 s10, s10, 4
	s_mul_hi_i32 s9, s10, 0x800
	s_mul_i32 s10, s10, 0x800
	s_and_b32 s8, s8, 1
	s_lshl_b32 s8, s8, 6
	s_sub_u32 s10, s10, s8
	s_subb_u32 s9, s9, 0
	s_add_u32 s4, s4, s10
	s_addc_u32 s5, s5, s9
	s_add_u32 s6, s6, s10
	s_addc_u32 s7, s7, s9
	s_cmp_eq_u32 s101, 0
	s_cbranch_scc0 .Lkl_1085_s1
	v_readfirstlane_b32 s10, v142
	s_nop 3
	s_mul_i32 s8, s10, 8
	s_mul_i32 s9, s10, 0
	s_add_i32 s9, s9, 0x8000
	s_cmp_ge_u32 s10, 0x1000
	s_cselect_b32 s10, s9, s8
	s_xor_b32 s8, s3, 0x10000
	s_add_i32 s10, s10, s8
	s_add_i32 m0, s10, 0x1000
	s_add_u32 s8, s4, 0x1000
	s_addc_u32 s9, s5, 0x0
	global_load_lds_dwordx4 v238, s[8:9] offset:-4096
	s_add_u32 s8, s4, 0xc40
	s_addc_u32 s9, s5, 0x0
	global_load_lds_dwordx4 v238, s[8:9] offset:-3072

; #define WAIT_V0() asm volatile("s_waitcnt vmcnt(0)" ::: "memory")
; #define SBAR() __builtin_amdgcn_sched_barrier(0)
; template <int EPI>
; DEVI void gemm_tile(const u16* __restrict__ Ab, long lda, const u16* __restrict__ Bb, long ldb, int K, const EpiArgs& e,
;                     bool have0 = false, const u16* __restrict__ nA = nullptr, const u16* __restrict__ nB = nullptr) {
;     ...
;   for (int t = 0; t < nt; ++t) {
;     const int cur = t & 1;
;     if (t + 1 < nt) GLDS_STAGE(cur ^ 1, t + 1);
;     else if (nA) {
; #pragma unroll
;       for (int i = 0; i < GL; ++i) {
;         __builtin_amdgcn_global_load_lds((const unsigned*)(nA + (long)i * 64 * lda + toffA), (unsigned*)(g_shm + wid * 1024 + i * 8192), 16, 0, 0);
;         __builtin_amdgcn_global_load_lds((const unsigned*)(nB + (long)i * 64 * ldb + toffB), (unsigned*)(g_shm + TILE_B + wid * 1024 + i * 8192), 16, 0, 0);
;       }
;     }
;     const char* sb = g_shm + cur * STAGE_B;
; #pragma unroll
;     for (int ks = 0; ks < 2; ++ks) {
;       bf16x8 Bf[4];
; #pragma unroll
;       for (int n = 0; n < 4; ++n) Bf[n] = *(const bf16x8*)(sb + b_base + n * 2048 + ks * 1024);
; #pragma unroll
;       for (int mh = 0; mh < 2; ++mh) {
;         bf16x8 At[4];
; #pragma unroll
;         for (int m = 0; m < 4; ++m) At[m] = *(const bf16x8*)(sb + a_base + (mh * 4 + m) * 2048 + ks * 1024);
;         __builtin_amdgcn_s_setprio(1);
; #pragma unroll
;         for (int m = 0; m < 4; ++m)
; #pragma unroll
;           for (int n = 0; n < 4; ++n) acc[mh * 4 + m][n] = __builtin_amdgcn_mfma_f32_16x16x32_bf16(Bf[n], At[m], acc[mh * 4 + m][n], 0, 0, 0);
;         __builtin_amdgcn_s_setprio(0);
;       }
;       SBAR();
;     }
;     if (t + 1 < nt) { WAIT_V0(); __syncthreads(); }
;   }
.Lkl_1085_s8:
	s_waitcnt lgkmcnt(6)
	v_mfma_f32_16x16x32_bf16 v[46:49], v[150:153], v[174:177], v[46:49]
	v_mfma_f32_16x16x32_bf16 v[42:45], v[154:157], v[174:177], v[42:45]
	v_mfma_f32_16x16x32_bf16 v[38:41], v[158:161], v[174:177], v[38:41]
	v_mfma_f32_16x16x32_bf16 v[34:37], v[162:165], v[174:177], v[34:37]
	ds_read_b128 v[174:177], v178 offset:3072
	s_waitcnt lgkmcnt(5)
	v_mfma_f32_16x16x32_bf16 v[30:33], v[150:153], v[192:195], v[30:33]
	v_mfma_f32_16x16x32_bf16 v[26:29], v[154:157], v[192:195], v[26:29]
	v_mfma_f32_16x16x32_bf16 v[22:25], v[158:161], v[192:195], v[22:25]
	v_mfma_f32_16x16x32_bf16 v[18:21], v[162:165], v[192:195], v[18:21]
	ds_read_b128 v[192:195], v178 offset:5120
	s_waitcnt lgkmcnt(4)
	v_mfma_f32_16x16x32_bf16 v[14:17], v[150:153], v[198:201], v[14:17]
	v_mfma_f32_16x16x32_bf16 v[10:13], v[154:157], v[198:201], v[10:13]
	v_mfma_f32_16x16x32_bf16 v[6:9], v[158:161], v[198:201], v[6:9]
	v_mfma_f32_16x16x32_bf16 v[2:5], v[162:165], v[198:201], v[2:5]
	ds_read_b128 v[198:201], v178 offset:7168
	s_waitcnt lgkmcnt(3)
	v_mfma_f32_16x16x32_bf16 v[126:129], v[222:225], v[170:173], v[126:129]
	v_mfma_f32_16x16x32_bf16 v[122:125], v[226:229], v[170:173], v[122:125]
	v_mfma_f32_16x16x32_bf16 v[118:121], v[230:233], v[170:173], v[118:121]
	v_mfma_f32_16x16x32_bf16 v[114:117], v[234:237], v[170:173], v[114:117]
	ds_read_b128 v[170:173], v178 offset:9216
	s_waitcnt lgkmcnt(3)
	v_mfma_f32_16x16x32_bf16 v[110:113], v[222:225], v[174:177], v[110:113]
	v_mfma_f32_16x16x32_bf16 v[106:109], v[226:229], v[174:177], v[106:109]
	v_mfma_f32_16x16x32_bf16 v[102:105], v[230:233], v[174:177], v[102:105]
	v_mfma_f32_16x16x32_bf16 v[98:101], v[234:237], v[174:177], v[98:101]
	ds_read_b128 v[174:177], v178 offset:11264
	s_waitcnt lgkmcnt(3)
	v_mfma_f32_16x16x32_bf16 v[94:97], v[222:225], v[192:195], v[94:97]
	v_mfma_f32_16x16x32_bf16 v[90:93], v[226:229], v[192:195], v[90:93]
	v_mfma_f32_16x16x32_bf16 v[86:89], v[230:233], v[192:195], v[86:89]
	v_mfma_f32_16x16x32_bf16 v[82:85], v[234:237], v[192:195], v[82:85]
	ds_read_b128 v[192:195], v178 offset:13312
	s_waitcnt lgkmcnt(3)
	v_mfma_f32_16x16x32_bf16 v[78:81], v[222:225], v[198:201], v[78:81]
	v_mfma_f32_16x16x32_bf16 v[74:77], v[226:229], v[198:201], v[74:77]
	v_mfma_f32_16x16x32_bf16 v[70:73], v[230:233], v[198:201], v[70:73]
	v_mfma_f32_16x16x32_bf16 v[66:69], v[234:237], v[198:201], v[66:69]
	ds_read_b128 v[198:201], v178 offset:15360
	s_waitcnt lgkmcnt(3)
	v_mfma_f32_16x16x32_bf16 v[62:65], v[222:225], v[170:173], v[62:65]
	v_mfma_f32_16x16x32_bf16 v[58:61], v[226:229], v[170:173], v[58:61]
	v_mfma_f32_16x16x32_bf16 v[54:57], v[230:233], v[170:173], v[54:57]
	v_mfma_f32_16x16x32_bf16 v[50:53], v[234:237], v[170:173], v[50:53]
	s_waitcnt lgkmcnt(2)
	v_mfma_f32_16x16x32_bf16 v[46:49], v[222:225], v[174:177], v[46:49]
	v_mfma_f32_16x16x32_bf16 v[42:45], v[226:229], v[174:177], v[42:45]
	v_mfma_f32_16x16x32_bf16 v[38:41], v[230:233], v[174:177], v[38:41]
	v_mfma_f32_16x16x32_bf16 v[34:37], v[234:237], v[174:177], v[34:37]
	s_waitcnt lgkmcnt(0)
	s_waitcnt vmcnt(0)
	s_add_u32 s16, s16, 0x80
	s_addc_u32 s17, s17, 0
	s_add_i32 s2, s2, 0x10000
	s_cmpk_eq_i32 s16, 0x780
	s_waitcnt vmcnt(0)
	s_barrier
	s_cselect_b32 s100, 1, 0
	s_and_b32 s3, s2, 0x10000
	v_or_b32_e32 v150, s3, v149
	v_add_u32_e32 v169, v150, v148
	v_or_b32_e32 v150, s3, v146
	v_add_u32_e32 v178, v150, v147
	ds_read_b128 v[150:153], v169 offset:32768
	ds_read_b128 v[154:157], v169 offset:34816
	ds_read_b128 v[158:161], v169 offset:36864
	ds_read_b128 v[162:165], v169 offset:38912
	ds_read_b128 v[170:173], v178
	ds_read_b128 v[174:177], v178 offset:2048
	s_add_u32 s4, s4, 0x80
	s_addc_u32 s5, s5, 0
	s_add_u32 s6, s6, 0x80
	s_addc_u32 s7, s7, 0
	s_cmp_eq_u32 s100, 1
	s_cbranch_scc1 .Lkl_1085_s9
	s_cmp_eq_u32 s101, 0
	s_cbranch_scc0 .Lkl_1085_s9
	v_readfirstlane_b32 s10, v142
	s_nop 3
	s_mul_i32 s8, s10, 8
	s_mul_i32 s9, s10, 0
	s_add_i32 s9, s9, 0x8000
	s_cmp_ge_u32 s10, 0x1000
	s_cselect_b32 s10, s9, s8
	s_xor_b32 s8, s3, 0x10000
	s_add_i32 s10, s10, s8
	s_add_i32 m0, s10, 0x1000
	s_add_u32 s8, s4, 0x1000
	s_addc_u32 s9, s5, 0x0
	global_load_lds_dwordx4 v238, s[8:9] offset:-4096
	s_add_u32 s8, s4, 0xc40
	s_addc_u32 s9, s5, 0x0
	global_load_lds_dwordx4 v238, s[8:9] offset:-3072

; #define WAIT_V0() asm volatile("s_waitcnt vmcnt(0)" ::: "memory")
; #define SBAR() __builtin_amdgcn_sched_barrier(0)
; template <int EPI>
; DEVI void gemm_tile(const u16* __restrict__ Ab, long lda, const u16* __restrict__ Bb, long ldb, int K, const EpiArgs& e,
;                     bool have0 = false, const u16* __restrict__ nA = nullptr, const u16* __restrict__ nB = nullptr) {
;     ...
;   f32x4 acc[8][4];
; #pragma unroll
;   for (int m = 0; m < 8; ++m)
; #pragma unroll
;     for (int n = 0; n < 4; ++n) acc[m][n] = f32x4{0.f, 0.f, 0.f, 0.f};
;   const int nt = K / BK;
;   if (!have0) GLDS_STAGE(0, 0);
;   WAIT_V0(); __syncthreads();
;   for (int t = 0; t < nt; ++t) {
;     const int cur = t & 1;
;     if (t + 1 < nt) GLDS_STAGE(cur ^ 1, t + 1);
;     else if (nA) {
; #pragma unroll
;       for (int i = 0; i < GL; ++i) {
;         __builtin_amdgcn_global_load_lds((const unsigned*)(nA + (long)i * 64 * lda + toffA), (unsigned*)(g_shm + wid * 1024 + i * 8192), 16, 0, 0);
;         __builtin_amdgcn_global_load_lds((const unsigned*)(nB + (long)i * 64 * ldb + toffB), (unsigned*)(g_shm + TILE_B + wid * 1024 + i * 8192), 16, 0, 0);
;       }
;     }
;     const char* sb = g_shm + cur * STAGE_B;
; #pragma unroll
;     for (int ks = 0; ks < 2; ++ks) {
;       bf16x8 Bf[4];
; #pragma unroll
;       for (int n = 0; n < 4; ++n) Bf[n] = *(const bf16x8*)(sb + b_base + n * 2048 + ks * 1024);
; #pragma unroll
;       for (int mh = 0; mh < 2; ++mh) {
;         bf16x8 At[4];
; #pragma unroll
;         for (int m = 0; m < 4; ++m) At[m] = *(const bf16x8*)(sb + a_base + (mh * 4 + m) * 2048 + ks * 1024);
;         __builtin_amdgcn_s_setprio(1);
; #pragma unroll
;         for (int m = 0; m < 4; ++m)
; #pragma unroll
;           for (int n = 0; n < 4; ++n) acc[mh * 4 + m][n] = __builtin_amdgcn_mfma_f32_16x16x32_bf16(Bf[n], At[m], acc[mh * 4 + m][n], 0, 0, 0);
;         __builtin_amdgcn_s_setprio(0);
;       }
;       SBAR();
;     }
;     if (t + 1 < nt) { WAIT_V0(); __syncthreads(); }
;   }
.LBB0_1121:
	s_and_b32 s3, s2, 0x10000
	v_or_b32_e32 v150, s3, v149
	v_add_u32_e32 v169, v150, v148
	v_or_b32_e32 v150, s3, v146
	v_add_u32_e32 v178, v150, v147
	ds_read_b128 v[150:153], v169 offset:32768
	ds_read_b128 v[154:157], v169 offset:34816
	ds_read_b128 v[158:161], v169 offset:36864
	ds_read_b128 v[162:165], v169 offset:38912
	ds_read_b128 v[170:173], v178
	ds_read_b128 v[174:177], v178 offset:2048
	ds_read_b128 v[214:217], v178 offset:4096
	ds_read_b128 v[218:221], v178 offset:6144
	v_writelane_b32 v240, s4, 0
	v_writelane_b32 v240, s5, 1
	v_writelane_b32 v240, s6, 2
	v_writelane_b32 v240, s7, 3
	v_writelane_b32 v240, s8, 4
	v_writelane_b32 v240, s9, 5
	v_writelane_b32 v240, s10, 6
	v_readfirstlane_b32 s4, v132
	v_readfirstlane_b32 s5, v133
	s_nop 1
	v_subrev_u32_e32 v238, s4, v132
	s_add_u32 s4, s4, s16
	s_addc_u32 s5, s5, s17
	v_readfirstlane_b32 s6, v134
	v_readfirstlane_b32 s7, v135
	s_nop 1
	v_subrev_u32_e32 v239, s6, v134
	s_add_u32 s6, s6, s16
	s_addc_u32 s7, s7, s17
	s_add_u32 s4, s4, s30
	s_addc_u32 s5, s5, s31
	s_add_u32 s6, s6, 0x8400080
	s_addc_u32 s7, s7, 0
	v_readfirstlane_b32 s8, v142
	s_nop 3
	s_lshr_b32 s8, s8, 10
	s_mul_i32 s9, s8, 4
	s_mul_i32 s10, s8, 0
	s_add_i32 s10, s10, 16
	s_cmp_ge_u32 s8, 4
	s_cselect_b32 s10, s10, s9
	s_lshr_b32 s9, s8, 1
	s_sub_i32 s10, s10, s9
	s_lshl_b32 s10, s10, 4
	s_mul_hi_i32 s9, s10, 0x800
	s_mul_i32 s10, s10, 0x800
	s_and_b32 s8, s8, 1
	s_lshl_b32 s8, s8, 6
	s_sub_u32 s10, s10, s8
	s_subb_u32 s9, s9, 0
	s_add_u32 s4, s4, s10
	s_addc_u32 s5, s5, s9
	s_add_u32 s6, s6, s10
	s_addc_u32 s7, s7, s9
	s_cmp_eq_u32 s101, 0
	s_cbranch_scc0 .Lkl_1121_s1
	v_readfirstlane_b32 s10, v142
	s_nop 3
	s_mul_i32 s8, s10, 8
	s_mul_i32 s9, s10, 0
	s_add_i32 s9, s9, 0x8000
	s_cmp_ge_u32 s10, 0x1000
	s_cselect_b32 s10, s9, s8
	s_xor_b32 s8, s3, 0x10000
	s_add_i32 s10, s10, s8
	s_add_i32 m0, s10, 0x1000
	s_add_u32 s8, s4, 0x1000
	s_addc_u32 s9, s5, 0x0
	global_load_lds_dwordx4 v238, s[8:9] offset:-4096
	s_add_u32 s8, s4, 0xc40
	s_addc_u32 s9, s5, 0x0
	global_load_lds_dwordx4 v238, s[8:9] offset:-3072

; #define WAIT_V0() asm volatile("s_waitcnt vmcnt(0)" ::: "memory")
; #define SBAR() __builtin_amdgcn_sched_barrier(0)
; template <int EPI>
; DEVI void gemm_tile(const u16* __restrict__ Ab, long lda, const u16* __restrict__ Bb, long ldb, int K, const EpiArgs& e,
;                     bool have0 = false, const u16* __restrict__ nA = nullptr, const u16* __restrict__ nB = nullptr) {
;     ...
;   f32x4 acc[8][4];
; #pragma unroll
;   for (int m = 0; m < 8; ++m)
; #pragma unroll
;     for (int n = 0; n < 4; ++n) acc[m][n] = f32x4{0.f, 0.f, 0.f, 0.f};
;   const int nt = K / BK;
;   if (!have0) GLDS_STAGE(0, 0);
;   WAIT_V0(); __syncthreads();
;   for (int t = 0; t < nt; ++t) {
;     const int cur = t & 1;
;     if (t + 1 < nt) GLDS_STAGE(cur ^ 1, t + 1);
;     else if (nA) {
; #pragma unroll
;       for (int i = 0; i < GL; ++i) {
;         __builtin_amdgcn_global_load_lds((const unsigned*)(nA + (long)i * 64 * lda + toffA), (unsigned*)(g_shm + wid * 1024 + i * 8192), 16, 0, 0);
;         __builtin_amdgcn_global_load_lds((const unsigned*)(nB + (long)i * 64 * ldb + toffB), (unsigned*)(g_shm + TILE_B + wid * 1024 + i * 8192), 16, 0, 0);
;       }
;     }
;     const char* sb = g_shm + cur * STAGE_B;
; #pragma unroll
;     for (int ks = 0; ks < 2; ++ks) {
;       bf16x8 Bf[4];
; #pragma unroll
;       for (int n = 0; n < 4; ++n) Bf[n] = *(const bf16x8*)(sb + b_base + n * 2048 + ks * 1024);
; #pragma unroll
;       for (int mh = 0; mh < 2; ++mh) {
;         bf16x8 At[4];
; #pragma unroll
;         for (int m = 0; m < 4; ++m) At[m] = *(const bf16x8*)(sb + a_base + (mh * 4 + m) * 2048 + ks * 1024);
;         __builtin_amdgcn_s_setprio(1);
; #pragma unroll
;         for (int m = 0; m < 4; ++m)
; #pragma unroll
;           for (int n = 0; n < 4; ++n) acc[mh * 4 + m][n] = __builtin_amdgcn_mfma_f32_16x16x32_bf16(Bf[n], At[m], acc[mh * 4 + m][n], 0, 0, 0);
;         __builtin_amdgcn_s_setprio(0);
;       }
;       SBAR();
;     }
;     if (t + 1 < nt) { WAIT_V0(); __syncthreads(); }
;   }
.Lkl_1121_s5:
	s_waitcnt lgkmcnt(5)
	v_mfma_f32_16x16x32_bf16 v[94:97], v[150:153], v[214:217], v[94:97]
	v_mfma_f32_16x16x32_bf16 v[90:93], v[154:157], v[214:217], v[90:93]
	v_mfma_f32_16x16x32_bf16 v[86:89], v[158:161], v[214:217], v[86:89]
	v_mfma_f32_16x16x32_bf16 v[82:85], v[162:165], v[214:217], v[82:85]
	ds_read_b128 v[214:217], v178 offset:12288
	ds_read_b128 v[230:233], v169 offset:37888
	s_cmp_eq_u32 s101, 0
	s_cbranch_scc0 .Lkl_1121_s6
	s_add_u32 s8, s6, 0x8800
	s_addc_u32 s9, s7, 0x0
	global_load_lds_dwordx4 v239, s[8:9] offset:-2048
	s_add_u32 s8, s6, 0x8440
	s_addc_u32 s9, s7, 0x0
	global_load_lds_dwordx4 v239, s[8:9] offset:-1024
.Lkl_1121_s6:
	s_waitcnt lgkmcnt(6)
	v_mfma_f32_16x16x32_bf16 v[78:81], v[150:153], v[218:221], v[78:81]
	v_mfma_f32_16x16x32_bf16 v[74:77], v[154:157], v[218:221], v[74:77]
	v_mfma_f32_16x16x32_bf16 v[70:73], v[158:161], v[218:221], v[70:73]
	v_mfma_f32_16x16x32_bf16 v[66:69], v[162:165], v[218:221], v[66:69]
	ds_read_b128 v[218:221], v178 offset:14336
	ds_read_b128 v[234:237], v169 offset:39936
	s_cmp_eq_u32 s101, 0
	s_cbranch_scc0 .Lkl_1121_s7
	s_add_u32 s8, s6, 0x10000
	s_addc_u32 s9, s7, 0x0
	global_load_lds_dwordx4 v239, s[8:9] offset:0
	s_add_u32 s8, s6, 0xfc40
	s_addc_u32 s9, s7, 0x0
	global_load_lds_dwordx4 v239, s[8:9] offset:1024

; #define WAIT_V0() asm volatile("s_waitcnt vmcnt(0)" ::: "memory")
; #define SBAR() __builtin_amdgcn_sched_barrier(0)
; template <int EPI>
; DEVI void gemm_tile(const u16* __restrict__ Ab, long lda, const u16* __restrict__ Bb, long ldb, int K, const EpiArgs& e,
;                     bool have0 = false, const u16* __restrict__ nA = nullptr, const u16* __restrict__ nB = nullptr) {
;     ...
;   for (int t = 0; t < nt; ++t) {
;     const int cur = t & 1;
;     if (t + 1 < nt) GLDS_STAGE(cur ^ 1, t + 1);
;     else if (nA) {
; #pragma unroll
;       for (int i = 0; i < GL; ++i) {
;         __builtin_amdgcn_global_load_lds((const unsigned*)(nA + (long)i * 64 * lda + toffA), (unsigned*)(g_shm + wid * 1024 + i * 8192), 16, 0, 0);
;         __builtin_amdgcn_global_load_lds((const unsigned*)(nB + (long)i * 64 * ldb + toffB), (unsigned*)(g_shm + TILE_B + wid * 1024 + i * 8192), 16, 0, 0);
;       }
;     }
;     const char* sb = g_shm + cur * STAGE_B;
; #pragma unroll
;     for (int ks = 0; ks < 2; ++ks) {
;       bf16x8 Bf[4];
; #pragma unroll
;       for (int n = 0; n < 4; ++n) Bf[n] = *(const bf16x8*)(sb + b_base + n * 2048 + ks * 1024);
; #pragma unroll
;       for (int mh = 0; mh < 2; ++mh) {
;         bf16x8 At[4];
; #pragma unroll
;         for (int m = 0; m < 4; ++m) At[m] = *(const bf16x8*)(sb + a_base + (mh * 4 + m) * 2048 + ks * 1024);
;         __builtin_amdgcn_s_setprio(1);
; #pragma unroll
;         for (int m = 0; m < 4; ++m)
; #pragma unroll
;           for (int n = 0; n < 4; ++n) acc[mh * 4 + m][n] = __builtin_amdgcn_mfma_f32_16x16x32_bf16(Bf[n], At[m], acc[mh * 4 + m][n], 0, 0, 0);
;         __builtin_amdgcn_s_setprio(0);
;       }
;       SBAR();
;     }
;     if (t + 1 < nt) { WAIT_V0(); __syncthreads(); }
;   }
.Lkl_1121_s8:
	s_waitcnt lgkmcnt(6)
	v_mfma_f32_16x16x32_bf16 v[46:49], v[150:153], v[174:177], v[46:49]
	v_mfma_f32_16x16x32_bf16 v[42:45], v[154:157], v[174:177], v[42:45]
	v_mfma_f32_16x16x32_bf16 v[38:41], v[158:161], v[174:177], v[38:41]
	v_mfma_f32_16x16x32_bf16 v[34:37], v[162:165], v[174:177], v[34:37]
	ds_read_b128 v[174:177], v178 offset:3072
	s_waitcnt lgkmcnt(5)
	v_mfma_f32_16x16x32_bf16 v[30:33], v[150:153], v[214:217], v[30:33]
	v_mfma_f32_16x16x32_bf16 v[26:29], v[154:157], v[214:217], v[26:29]
	v_mfma_f32_16x16x32_bf16 v[22:25], v[158:161], v[214:217], v[22:25]
	v_mfma_f32_16x16x32_bf16 v[18:21], v[162:165], v[214:217], v[18:21]
	ds_read_b128 v[214:217], v178 offset:5120
	s_waitcnt lgkmcnt(4)
	v_mfma_f32_16x16x32_bf16 v[14:17], v[150:153], v[218:221], v[14:17]
	v_mfma_f32_16x16x32_bf16 v[10:13], v[154:157], v[218:221], v[10:13]
	v_mfma_f32_16x16x32_bf16 v[6:9], v[158:161], v[218:221], v[6:9]
	v_mfma_f32_16x16x32_bf16 v[2:5], v[162:165], v[218:221], v[2:5]
	ds_read_b128 v[218:221], v178 offset:7168
	s_waitcnt lgkmcnt(3)
	v_mfma_f32_16x16x32_bf16 v[126:129], v[222:225], v[170:173], v[126:129]
	v_mfma_f32_16x16x32_bf16 v[122:125], v[226:229], v[170:173], v[122:125]
	v_mfma_f32_16x16x32_bf16 v[118:121], v[230:233], v[170:173], v[118:121]
	v_mfma_f32_16x16x32_bf16 v[114:117], v[234:237], v[170:173], v[114:117]
	ds_read_b128 v[170:173], v178 offset:9216
	s_waitcnt lgkmcnt(3)
	v_mfma_f32_16x16x32_bf16 v[110:113], v[222:225], v[174:177], v[110:113]
	v_mfma_f32_16x16x32_bf16 v[106:109], v[226:229], v[174:177], v[106:109]
	v_mfma_f32_16x16x32_bf16 v[102:105], v[230:233], v[174:177], v[102:105]
	v_mfma_f32_16x16x32_bf16 v[98:101], v[234:237], v[174:177], v[98:101]
	ds_read_b128 v[174:177], v178 offset:11264
	s_waitcnt lgkmcnt(3)
	v_mfma_f32_16x16x32_bf16 v[94:97], v[222:225], v[214:217], v[94:97]
	v_mfma_f32_16x16x32_bf16 v[90:93], v[226:229], v[214:217], v[90:93]
	v_mfma_f32_16x16x32_bf16 v[86:89], v[230:233], v[214:217], v[86:89]
	v_mfma_f32_16x16x32_bf16 v[82:85], v[234:237], v[214:217], v[82:85]
	ds_read_b128 v[214:217], v178 offset:13312
	s_waitcnt lgkmcnt(3)
	v_mfma_f32_16x16x32_bf16 v[78:81], v[222:225], v[218:221], v[78:81]
	v_mfma_f32_16x16x32_bf16 v[74:77], v[226:229], v[218:221], v[74:77]
	v_mfma_f32_16x16x32_bf16 v[70:73], v[230:233], v[218:221], v[70:73]
	v_mfma_f32_16x16x32_bf16 v[66:69], v[234:237], v[218:221], v[66:69]
	ds_read_b128 v[218:221], v178 offset:15360
	s_waitcnt lgkmcnt(3)
	v_mfma_f32_16x16x32_bf16 v[62:65], v[222:225], v[170:173], v[62:65]
	v_mfma_f32_16x16x32_bf16 v[58:61], v[226:229], v[170:173], v[58:61]
	v_mfma_f32_16x16x32_bf16 v[54:57], v[230:233], v[170:173], v[54:57]
	v_mfma_f32_16x16x32_bf16 v[50:53], v[234:237], v[170:173], v[50:53]
	s_waitcnt lgkmcnt(2)
	v_mfma_f32_16x16x32_bf16 v[46:49], v[222:225], v[174:177], v[46:49]
	v_mfma_f32_16x16x32_bf16 v[42:45], v[226:229], v[174:177], v[42:45]
	v_mfma_f32_16x16x32_bf16 v[38:41], v[230:233], v[174:177], v[38:41]
	v_mfma_f32_16x16x32_bf16 v[34:37], v[234:237], v[174:177], v[34:37]
	s_waitcnt lgkmcnt(0)
	s_waitcnt vmcnt(0)
	s_add_u32 s16, s16, 0x80
	s_addc_u32 s17, s17, 0
	s_add_i32 s2, s2, 0x10000
	s_cmpk_eq_i32 s16, 0x780
	s_waitcnt vmcnt(0)
	s_barrier
	s_cselect_b32 s100, 1, 0
	s_and_b32 s3, s2, 0x10000
	v_or_b32_e32 v150, s3, v149
	v_add_u32_e32 v169, v150, v148
	v_or_b32_e32 v150, s3, v146
	v_add_u32_e32 v178, v150, v147
	ds_read_b128 v[150:153], v169 offset:32768
	ds_read_b128 v[154:157], v169 offset:34816
	ds_read_b128 v[158:161], v169 offset:36864
	ds_read_b128 v[162:165], v169 offset:38912
	ds_read_b128 v[170:173], v178
	ds_read_b128 v[174:177], v178 offset:2048
	s_add_u32 s4, s4, 0x80
	s_addc_u32 s5, s5, 0
	s_add_u32 s6, s6, 0x80
	s_addc_u32 s7, s7, 0
	s_cmp_eq_u32 s100, 1
	s_cbranch_scc1 .Lkl_1121_s9
	s_cmp_eq_u32 s101, 0
	s_cbranch_scc0 .Lkl_1121_s9
	v_readfirstlane_b32 s10, v142
	s_nop 3
	s_mul_i32 s8, s10, 8
	s_mul_i32 s9, s10, 0
	s_add_i32 s9, s9, 0x8000
	s_cmp_ge_u32 s10, 0x1000
	s_cselect_b32 s10, s9, s8
	s_xor_b32 s8, s3, 0x10000
	s_add_i32 s10, s10, s8
	s_add_i32 m0, s10, 0x1000
	s_add_u32 s8, s4, 0x1000
	s_addc_u32 s9, s5, 0x0
	global_load_lds_dwordx4 v238, s[8:9] offset:-4096
	s_add_u32 s8, s4, 0xc40
	s_addc_u32 s9, s5, 0x0
	global_load_lds_dwordx4 v238, s[8:9] offset:-3072
.Lkl_1121_s9:
	v_mfma_f32_16x16x32_bf16 v[30:33], v[222:225], v[214:217], v[30:33]
	v_mfma_f32_16x16x32_bf16 v[26:29], v[226:229], v[214:217], v[26:29]
	v_mfma_f32_16x16x32_bf16 v[22:25], v[230:233], v[214:217], v[22:25]
	v_mfma_f32_16x16x32_bf16 v[18:21], v[234:237], v[214:217], v[18:21]
	ds_read_b128 v[214:217], v178 offset:4096
	s_cmp_eq_u32 s100, 1
	s_cbranch_scc1 .Lkl_1121_s10
	s_cmp_eq_u32 s101, 0
	s_cbranch_scc0 .Lkl_1121_s10
	s_add_u32 s8, s4, 0x8800
	s_addc_u32 s9, s5, 0x0
	global_load_lds_dwordx4 v238, s[8:9] offset:-2048
	s_add_u32 s8, s4, 0x8440
	s_addc_u32 s9, s5, 0x0
	global_load_lds_dwordx4 v238, s[8:9] offset:-1024
.Lkl_1121_s10:
	v_mfma_f32_16x16x32_bf16 v[14:17], v[222:225], v[218:221], v[14:17]
	v_mfma_f32_16x16x32_bf16 v[10:13], v[226:229], v[218:221], v[10:13]
	v_mfma_f32_16x16x32_bf16 v[6:9], v[230:233], v[218:221], v[6:9]
	v_mfma_f32_16x16x32_bf16 v[2:5], v[234:237], v[218:221], v[2:5]
	ds_read_b128 v[218:221], v178 offset:6144
	s_cmp_eq_u32 s100, 1
	s_cbranch_scc1 .Lkl_1121_s11
	s_cmp_eq_u32 s101, 0
	s_cbranch_scc0 .Lkl_1121_s11
	s_add_u32 s8, s4, 0x10000
	s_addc_u32 s9, s5, 0x0
	global_load_lds_dwordx4 v238, s[8:9] offset:0
	s_add_u32 s8, s4, 0xfc40
	s_addc_u32 s9, s5, 0x0
	global_load_lds_dwordx4 v238, s[8:9] offset:1024

; #define WAIT_V0() asm volatile("s_waitcnt vmcnt(0)" ::: "memory")
; #define SBAR() __builtin_amdgcn_sched_barrier(0)
; template <int EPI>
; DEVI void gemm_tile(const u16* __restrict__ Ab, long lda, const u16* __restrict__ Bb, long ldb, int K, const EpiArgs& e,
;                     bool have0 = false, const u16* __restrict__ nA = nullptr, const u16* __restrict__ nB = nullptr) {
;     ...
;   f32x4 acc[8][4];
; #pragma unroll
;   for (int m = 0; m < 8; ++m)
; #pragma unroll
;     for (int n = 0; n < 4; ++n) acc[m][n] = f32x4{0.f, 0.f, 0.f, 0.f};
;   const int nt = K / BK;
;   if (!have0) GLDS_STAGE(0, 0);
;   WAIT_V0(); __syncthreads();
;   for (int t = 0; t < nt; ++t) {
;     const int cur = t & 1;
;     if (t + 1 < nt) GLDS_STAGE(cur ^ 1, t + 1);
;     else if (nA) {
; #pragma unroll
;       for (int i = 0; i < GL; ++i) {
;         __builtin_amdgcn_global_load_lds((const unsigned*)(nA + (long)i * 64 * lda + toffA), (unsigned*)(g_shm + wid * 1024 + i * 8192), 16, 0, 0);
;         __builtin_amdgcn_global_load_lds((const unsigned*)(nB + (long)i * 64 * ldb + toffB), (unsigned*)(g_shm + TILE_B + wid * 1024 + i * 8192), 16, 0, 0);
;       }
;     }
;     const char* sb = g_shm + cur * STAGE_B;
; #pragma unroll
;     for (int ks = 0; ks < 2; ++ks) {
;       bf16x8 Bf[4];
; #pragma unroll
;       for (int n = 0; n < 4; ++n) Bf[n] = *(const bf16x8*)(sb + b_base + n * 2048 + ks * 1024);
; #pragma unroll
;       for (int mh = 0; mh < 2; ++mh) {
;         bf16x8 At[4];
; #pragma unroll
;         for (int m = 0; m < 4; ++m) At[m] = *(const bf16x8*)(sb + a_base + (mh * 4 + m) * 2048 + ks * 1024);
;         __builtin_amdgcn_s_setprio(1);
; #pragma unroll
;         for (int m = 0; m < 4; ++m)
; #pragma unroll
;           for (int n = 0; n < 4; ++n) acc[mh * 4 + m][n] = __builtin_amdgcn_mfma_f32_16x16x32_bf16(Bf[n], At[m], acc[mh * 4 + m][n], 0, 0, 0);
;         __builtin_amdgcn_s_setprio(0);
;       }
;       SBAR();
;     }
;     if (t + 1 < nt) { WAIT_V0(); __syncthreads(); }
;   }
.LBB0_1302:
	s_and_b32 s3, s2, 0x10000
	v_or_b32_e32 v150, s3, v149
	v_add_u32_e32 v169, v150, v148
	v_or_b32_e32 v150, s3, v146
	v_add_u32_e32 v178, v150, v147
	ds_read_b128 v[150:153], v169 offset:32768
	ds_read_b128 v[154:157], v169 offset:34816
	ds_read_b128 v[158:161], v169 offset:36864
	ds_read_b128 v[162:165], v169 offset:38912
	ds_read_b128 v[170:173], v178
	ds_read_b128 v[174:177], v178 offset:2048
	ds_read_b128 v[214:217], v178 offset:4096
	ds_read_b128 v[218:221], v178 offset:6144
	v_writelane_b32 v240, s4, 0
	v_writelane_b32 v240, s5, 1
	v_writelane_b32 v240, s6, 2
	v_writelane_b32 v240, s7, 3
	v_writelane_b32 v240, s8, 4
	v_writelane_b32 v240, s9, 5
	v_writelane_b32 v240, s10, 6
	v_readfirstlane_b32 s4, v134
	v_readfirstlane_b32 s5, v135
	s_nop 1
	v_subrev_u32_e32 v238, s4, v134
	s_add_u32 s4, s4, s16
	s_addc_u32 s5, s5, s17
	v_readfirstlane_b32 s6, v136
	v_readfirstlane_b32 s7, v137
	s_nop 1
	v_subrev_u32_e32 v239, s6, v136
	s_add_u32 s6, s6, s16
	s_addc_u32 s7, s7, s17
	s_add_u32 s4, s4, 0x1f500080
	s_addc_u32 s5, s5, 0
	s_add_u32 s6, s6, 0x87a0080
	s_addc_u32 s7, s7, 0
	v_readfirstlane_b32 s8, v142
	s_nop 3
	s_lshr_b32 s8, s8, 10
	s_mul_i32 s9, s8, 4
	s_mul_i32 s10, s8, 0
	s_add_i32 s10, s10, 16
	s_cmp_ge_u32 s8, 4
	s_cselect_b32 s10, s10, s9
	s_lshr_b32 s9, s8, 1
	s_sub_i32 s10, s10, s9
	s_lshl_b32 s10, s10, 4
	s_mul_hi_i32 s9, s10, 0x800
	s_mul_i32 s10, s10, 0x800
	s_and_b32 s8, s8, 1
	s_lshl_b32 s8, s8, 6
	s_sub_u32 s10, s10, s8
	s_subb_u32 s9, s9, 0
	s_add_u32 s4, s4, s10
	s_addc_u32 s5, s5, s9
	s_add_u32 s6, s6, s10
	s_addc_u32 s7, s7, s9
	s_cmp_eq_u32 s101, 0
	s_cbranch_scc0 .Lkl_1302_s1
	v_readfirstlane_b32 s10, v142
	s_nop 3
	s_mul_i32 s8, s10, 8
	s_mul_i32 s9, s10, 0
	s_add_i32 s9, s9, 0x8000
	s_cmp_ge_u32 s10, 0x1000
	s_cselect_b32 s10, s9, s8
	s_xor_b32 s8, s3, 0x10000
	s_add_i32 s10, s10, s8
	s_add_i32 m0, s10, 0x1000
	s_add_u32 s8, s4, 0x1000
	s_addc_u32 s9, s5, 0x0
	global_load_lds_dwordx4 v238, s[8:9] offset:-4096
	s_add_u32 s8, s4, 0xc40
	s_addc_u32 s9, s5, 0x0
	global_load_lds_dwordx4 v238, s[8:9] offset:-3072

; #define WAIT_V0() asm volatile("s_waitcnt vmcnt(0)" ::: "memory")
; #define SBAR() __builtin_amdgcn_sched_barrier(0)
; template <int EPI>
; DEVI void gemm_tile(const u16* __restrict__ Ab, long lda, const u16* __restrict__ Bb, long ldb, int K, const EpiArgs& e,
;                     bool have0 = false, const u16* __restrict__ nA = nullptr, const u16* __restrict__ nB = nullptr) {
;     ...
;   f32x4 acc[8][4];
; #pragma unroll
;   for (int m = 0; m < 8; ++m)
; #pragma unroll
;     for (int n = 0; n < 4; ++n) acc[m][n] = f32x4{0.f, 0.f, 0.f, 0.f};
;   const int nt = K / BK;
;   if (!have0) GLDS_STAGE(0, 0);
;   WAIT_V0(); __syncthreads();
;   for (int t = 0; t < nt; ++t) {
;     const int cur = t & 1;
;     if (t + 1 < nt) GLDS_STAGE(cur ^ 1, t + 1);
;     else if (nA) {
; #pragma unroll
;       for (int i = 0; i < GL; ++i) {
;         __builtin_amdgcn_global_load_lds((const unsigned*)(nA + (long)i * 64 * lda + toffA), (unsigned*)(g_shm + wid * 1024 + i * 8192), 16, 0, 0);
;         __builtin_amdgcn_global_load_lds((const unsigned*)(nB + (long)i * 64 * ldb + toffB), (unsigned*)(g_shm + TILE_B + wid * 1024 + i * 8192), 16, 0, 0);
;       }
;     }
;     const char* sb = g_shm + cur * STAGE_B;
; #pragma unroll
;     for (int ks = 0; ks < 2; ++ks) {
;       bf16x8 Bf[4];
; #pragma unroll
;       for (int n = 0; n < 4; ++n) Bf[n] = *(const bf16x8*)(sb + b_base + n * 2048 + ks * 1024);
; #pragma unroll
;       for (int mh = 0; mh < 2; ++mh) {
;         bf16x8 At[4];
; #pragma unroll
;         for (int m = 0; m < 4; ++m) At[m] = *(const bf16x8*)(sb + a_base + (mh * 4 + m) * 2048 + ks * 1024);
;         __builtin_amdgcn_s_setprio(1);
; #pragma unroll
;         for (int m = 0; m < 4; ++m)
; #pragma unroll
;           for (int n = 0; n < 4; ++n) acc[mh * 4 + m][n] = __builtin_amdgcn_mfma_f32_16x16x32_bf16(Bf[n], At[m], acc[mh * 4 + m][n], 0, 0, 0);
;         __builtin_amdgcn_s_setprio(0);
;       }
;       SBAR();
;     }
;     if (t + 1 < nt) { WAIT_V0(); __syncthreads(); }
;   }
.LBB0_1370:
	s_and_b32 s3, s2, 0x10000
	v_or_b32_e32 v149, s3, v147
	v_add_u32_e32 v169, v149, v148
	v_add_u32_e32 v149, v149, v146
	ds_read_b128 v[150:153], v169 offset:32768
	ds_read_b128 v[154:157], v169 offset:34816
	ds_read_b128 v[158:161], v169 offset:36864
	ds_read_b128 v[162:165], v169 offset:38912
	ds_read_b128 v[170:173], v149
	ds_read_b128 v[174:177], v149 offset:2048
	ds_read_b128 v[192:195], v149 offset:4096
	ds_read_b128 v[198:201], v149 offset:6144
	v_writelane_b32 v240, s4, 0
	v_writelane_b32 v240, s5, 1
	v_writelane_b32 v240, s6, 2
	v_writelane_b32 v240, s7, 3
	v_writelane_b32 v240, s8, 4
	v_writelane_b32 v240, s9, 5
	v_writelane_b32 v240, s10, 6
	v_readfirstlane_b32 s4, v132
	v_readfirstlane_b32 s5, v133
	s_nop 1
	v_subrev_u32_e32 v238, s4, v132
	s_add_u32 s4, s4, s18
	s_addc_u32 s5, s5, s19
	v_readfirstlane_b32 s6, v134
	v_readfirstlane_b32 s7, v135
	s_nop 1
	v_subrev_u32_e32 v239, s6, v134
	s_add_u32 s6, s6, s18
	s_addc_u32 s7, s7, s19
	s_add_u32 s4, s4, s12
	s_addc_u32 s5, s5, s13
	s_add_u32 s6, s6, 0xb00080
	s_addc_u32 s7, s7, 0
	v_readfirstlane_b32 s8, v140
	s_nop 3
	s_lshr_b32 s8, s8, 10
	s_mul_i32 s9, s8, 4
	s_mul_i32 s10, s8, 0
	s_add_i32 s10, s10, 16
	s_cmp_ge_u32 s8, 4
	s_cselect_b32 s10, s10, s9
	s_lshr_b32 s9, s8, 1
	s_sub_i32 s10, s10, s9
	s_lshl_b32 s10, s10, 4
	s_mul_hi_i32 s9, s10, 0x800
	s_mul_i32 s10, s10, 0x800
	s_and_b32 s8, s8, 1
	s_lshl_b32 s8, s8, 6
	s_sub_u32 s10, s10, s8
	s_subb_u32 s9, s9, 0
	s_add_u32 s4, s4, s10
	s_addc_u32 s5, s5, s9
	s_add_u32 s6, s6, s10
	s_addc_u32 s7, s7, s9
	s_cmp_eq_u32 s101, 0
	s_cbranch_scc0 .Lkl_1370_s1
	v_readfirstlane_b32 s10, v140
	s_nop 3
	s_mul_i32 s8, s10, 8
	s_mul_i32 s9, s10, 0
	s_add_i32 s9, s9, 0x8000
	s_cmp_ge_u32 s10, 0x1000
	s_cselect_b32 s10, s9, s8
	s_xor_b32 s8, s3, 0x10000
	s_add_i32 s10, s10, s8
	s_add_i32 m0, s10, 0x1000
	s_add_u32 s8, s4, 0x1000
	s_addc_u32 s9, s5, 0x0
	global_load_lds_dwordx4 v238, s[8:9] offset:-4096
	s_add_u32 s8, s4, 0xc40
	s_addc_u32 s9, s5, 0x0
	global_load_lds_dwordx4 v238, s[8:9] offset:-3072

; #define WAIT_V0() asm volatile("s_waitcnt vmcnt(0)" ::: "memory")
; #define SBAR() __builtin_amdgcn_sched_barrier(0)
; template <int EPI>
; DEVI void gemm_tile(const u16* __restrict__ Ab, long lda, const u16* __restrict__ Bb, long ldb, int K, const EpiArgs& e,
;                     bool have0 = false, const u16* __restrict__ nA = nullptr, const u16* __restrict__ nB = nullptr) {
;     ...
;   f32x4 acc[8][4];
; #pragma unroll
;   for (int m = 0; m < 8; ++m)
; #pragma unroll
;     for (int n = 0; n < 4; ++n) acc[m][n] = f32x4{0.f, 0.f, 0.f, 0.f};
;   const int nt = K / BK;
;   if (!have0) GLDS_STAGE(0, 0);
;   WAIT_V0(); __syncthreads();
;   for (int t = 0; t < nt; ++t) {
;     const int cur = t & 1;
;     if (t + 1 < nt) GLDS_STAGE(cur ^ 1, t + 1);
;     else if (nA) {
; #pragma unroll
;       for (int i = 0; i < GL; ++i) {
;         __builtin_amdgcn_global_load_lds((const unsigned*)(nA + (long)i * 64 * lda + toffA), (unsigned*)(g_shm + wid * 1024 + i * 8192), 16, 0, 0);
;         __builtin_amdgcn_global_load_lds((const unsigned*)(nB + (long)i * 64 * ldb + toffB), (unsigned*)(g_shm + TILE_B + wid * 1024 + i * 8192), 16, 0, 0);
;       }
;     }
;     const char* sb = g_shm + cur * STAGE_B;
; #pragma unroll
;     for (int ks = 0; ks < 2; ++ks) {
;       bf16x8 Bf[4];
; #pragma unroll
;       for (int n = 0; n < 4; ++n) Bf[n] = *(const bf16x8*)(sb + b_base + n * 2048 + ks * 1024);
; #pragma unroll
;       for (int mh = 0; mh < 2; ++mh) {
;         bf16x8 At[4];
; #pragma unroll
;         for (int m = 0; m < 4; ++m) At[m] = *(const bf16x8*)(sb + a_base + (mh * 4 + m) * 2048 + ks * 1024);
;         __builtin_amdgcn_s_setprio(1);
; #pragma unroll
;         for (int m = 0; m < 4; ++m)
; #pragma unroll
;           for (int n = 0; n < 4; ++n) acc[mh * 4 + m][n] = __builtin_amdgcn_mfma_f32_16x16x32_bf16(Bf[n], At[m], acc[mh * 4 + m][n], 0, 0, 0);
;         __builtin_amdgcn_s_setprio(0);
;       }
;       SBAR();
;     }
;     if (t + 1 < nt) { WAIT_V0(); __syncthreads(); }
;   }
.Lkl_1370_s5:
	s_waitcnt lgkmcnt(5)
	v_mfma_f32_16x16x32_bf16 v[94:97], v[150:153], v[192:195], v[94:97]
	v_mfma_f32_16x16x32_bf16 v[90:93], v[154:157], v[192:195], v[90:93]
	v_mfma_f32_16x16x32_bf16 v[86:89], v[158:161], v[192:195], v[86:89]
	v_mfma_f32_16x16x32_bf16 v[82:85], v[162:165], v[192:195], v[82:85]
	ds_read_b128 v[192:195], v149 offset:12288
	ds_read_b128 v[230:233], v169 offset:37888
	s_cmp_eq_u32 s101, 0
	s_cbranch_scc0 .Lkl_1370_s6
	s_add_u32 s8, s6, 0x8800
	s_addc_u32 s9, s7, 0x0
	global_load_lds_dwordx4 v239, s[8:9] offset:-2048
	s_add_u32 s8, s6, 0x8440
	s_addc_u32 s9, s7, 0x0
	global_load_lds_dwordx4 v239, s[8:9] offset:-1024
.Lkl_1370_s6:
	s_waitcnt lgkmcnt(6)
	v_mfma_f32_16x16x32_bf16 v[78:81], v[150:153], v[198:201], v[78:81]
	v_mfma_f32_16x16x32_bf16 v[74:77], v[154:157], v[198:201], v[74:77]
	v_mfma_f32_16x16x32_bf16 v[70:73], v[158:161], v[198:201], v[70:73]
	v_mfma_f32_16x16x32_bf16 v[66:69], v[162:165], v[198:201], v[66:69]
	ds_read_b128 v[198:201], v149 offset:14336
	ds_read_b128 v[234:237], v169 offset:39936
	s_cmp_eq_u32 s101, 0
	s_cbranch_scc0 .Lkl_1370_s7
	s_add_u32 s8, s6, 0x10000
	s_addc_u32 s9, s7, 0x0
	global_load_lds_dwordx4 v239, s[8:9] offset:0
	s_add_u32 s8, s6, 0xfc40
	s_addc_u32 s9, s7, 0x0
	global_load_lds_dwordx4 v239, s[8:9] offset:1024

; #define WAIT_V0() asm volatile("s_waitcnt vmcnt(0)" ::: "memory")
; #define SBAR() __builtin_amdgcn_sched_barrier(0)
; template <int EPI>
; DEVI void gemm_tile(const u16* __restrict__ Ab, long lda, const u16* __restrict__ Bb, long ldb, int K, const EpiArgs& e,
;                     bool have0 = false, const u16* __restrict__ nA = nullptr, const u16* __restrict__ nB = nullptr) {
;     ...
;   for (int t = 0; t < nt; ++t) {
;     const int cur = t & 1;
;     if (t + 1 < nt) GLDS_STAGE(cur ^ 1, t + 1);
;     else if (nA) {
; #pragma unroll
;       for (int i = 0; i < GL; ++i) {
;         __builtin_amdgcn_global_load_lds((const unsigned*)(nA + (long)i * 64 * lda + toffA), (unsigned*)(g_shm + wid * 1024 + i * 8192), 16, 0, 0);
;         __builtin_amdgcn_global_load_lds((const unsigned*)(nB + (long)i * 64 * ldb + toffB), (unsigned*)(g_shm + TILE_B + wid * 1024 + i * 8192), 16, 0, 0);
;       }
;     }
;     const char* sb = g_shm + cur * STAGE_B;
; #pragma unroll
;     for (int ks = 0; ks < 2; ++ks) {
;       bf16x8 Bf[4];
; #pragma unroll
;       for (int n = 0; n < 4; ++n) Bf[n] = *(const bf16x8*)(sb + b_base + n * 2048 + ks * 1024);
; #pragma unroll
;       for (int mh = 0; mh < 2; ++mh) {
;         bf16x8 At[4];
; #pragma unroll
;         for (int m = 0; m < 4; ++m) At[m] = *(const bf16x8*)(sb + a_base + (mh * 4 + m) * 2048 + ks * 1024);
;         __builtin_amdgcn_s_setprio(1);
; #pragma unroll
;         for (int m = 0; m < 4; ++m)
; #pragma unroll
;           for (int n = 0; n < 4; ++n) acc[mh * 4 + m][n] = __builtin_amdgcn_mfma_f32_16x16x32_bf16(Bf[n], At[m], acc[mh * 4 + m][n], 0, 0, 0);
;         __builtin_amdgcn_s_setprio(0);
;       }
;       SBAR();
;     }
;     if (t + 1 < nt) { WAIT_V0(); __syncthreads(); }
;   }
.Lkl_1370_s8:
	s_waitcnt lgkmcnt(6)
	v_mfma_f32_16x16x32_bf16 v[46:49], v[150:153], v[174:177], v[46:49]
	v_mfma_f32_16x16x32_bf16 v[42:45], v[154:157], v[174:177], v[42:45]
	v_mfma_f32_16x16x32_bf16 v[38:41], v[158:161], v[174:177], v[38:41]
	v_mfma_f32_16x16x32_bf16 v[34:37], v[162:165], v[174:177], v[34:37]
	ds_read_b128 v[174:177], v149 offset:3072
	s_waitcnt lgkmcnt(5)
	v_mfma_f32_16x16x32_bf16 v[30:33], v[150:153], v[192:195], v[30:33]
	v_mfma_f32_16x16x32_bf16 v[26:29], v[154:157], v[192:195], v[26:29]
	v_mfma_f32_16x16x32_bf16 v[22:25], v[158:161], v[192:195], v[22:25]
	v_mfma_f32_16x16x32_bf16 v[18:21], v[162:165], v[192:195], v[18:21]
	ds_read_b128 v[192:195], v149 offset:5120
	s_waitcnt lgkmcnt(4)
	v_mfma_f32_16x16x32_bf16 v[14:17], v[150:153], v[198:201], v[14:17]
	v_mfma_f32_16x16x32_bf16 v[10:13], v[154:157], v[198:201], v[10:13]
	v_mfma_f32_16x16x32_bf16 v[6:9], v[158:161], v[198:201], v[6:9]
	v_mfma_f32_16x16x32_bf16 v[2:5], v[162:165], v[198:201], v[2:5]
	ds_read_b128 v[198:201], v149 offset:7168
	s_waitcnt lgkmcnt(3)
	v_mfma_f32_16x16x32_bf16 v[126:129], v[222:225], v[170:173], v[126:129]
	v_mfma_f32_16x16x32_bf16 v[122:125], v[226:229], v[170:173], v[122:125]
	v_mfma_f32_16x16x32_bf16 v[118:121], v[230:233], v[170:173], v[118:121]
	v_mfma_f32_16x16x32_bf16 v[114:117], v[234:237], v[170:173], v[114:117]
	ds_read_b128 v[170:173], v149 offset:9216
	s_waitcnt lgkmcnt(3)
	v_mfma_f32_16x16x32_bf16 v[110:113], v[222:225], v[174:177], v[110:113]
	v_mfma_f32_16x16x32_bf16 v[106:109], v[226:229], v[174:177], v[106:109]
	v_mfma_f32_16x16x32_bf16 v[102:105], v[230:233], v[174:177], v[102:105]
	v_mfma_f32_16x16x32_bf16 v[98:101], v[234:237], v[174:177], v[98:101]
	ds_read_b128 v[174:177], v149 offset:11264
	s_waitcnt lgkmcnt(3)
	v_mfma_f32_16x16x32_bf16 v[94:97], v[222:225], v[192:195], v[94:97]
	v_mfma_f32_16x16x32_bf16 v[90:93], v[226:229], v[192:195], v[90:93]
	v_mfma_f32_16x16x32_bf16 v[86:89], v[230:233], v[192:195], v[86:89]
	v_mfma_f32_16x16x32_bf16 v[82:85], v[234:237], v[192:195], v[82:85]
	ds_read_b128 v[192:195], v149 offset:13312
	s_waitcnt lgkmcnt(3)
	v_mfma_f32_16x16x32_bf16 v[78:81], v[222:225], v[198:201], v[78:81]
	v_mfma_f32_16x16x32_bf16 v[74:77], v[226:229], v[198:201], v[74:77]
	v_mfma_f32_16x16x32_bf16 v[70:73], v[230:233], v[198:201], v[70:73]
	v_mfma_f32_16x16x32_bf16 v[66:69], v[234:237], v[198:201], v[66:69]
	ds_read_b128 v[198:201], v149 offset:15360
	s_waitcnt lgkmcnt(3)
	v_mfma_f32_16x16x32_bf16 v[62:65], v[222:225], v[170:173], v[62:65]
	v_mfma_f32_16x16x32_bf16 v[58:61], v[226:229], v[170:173], v[58:61]
	v_mfma_f32_16x16x32_bf16 v[54:57], v[230:233], v[170:173], v[54:57]
	v_mfma_f32_16x16x32_bf16 v[50:53], v[234:237], v[170:173], v[50:53]
	s_waitcnt lgkmcnt(2)
	v_mfma_f32_16x16x32_bf16 v[46:49], v[222:225], v[174:177], v[46:49]
	v_mfma_f32_16x16x32_bf16 v[42:45], v[226:229], v[174:177], v[42:45]
	v_mfma_f32_16x16x32_bf16 v[38:41], v[230:233], v[174:177], v[38:41]
	v_mfma_f32_16x16x32_bf16 v[34:37], v[234:237], v[174:177], v[34:37]
	s_waitcnt lgkmcnt(0)
	s_add_i32 s2, s2, 0x10000
	s_waitcnt vmcnt(0)
	s_add_u32 s18, s18, 0x80
	s_addc_u32 s19, s19, 0
	s_cmpk_eq_i32 s18, 0x780
	s_waitcnt vmcnt(0)
	s_barrier
	s_cselect_b32 s100, 1, 0
	s_and_b32 s3, s2, 0x10000
	v_or_b32_e32 v149, s3, v147
	v_add_u32_e32 v169, v149, v148
	v_add_u32_e32 v149, v149, v146
	ds_read_b128 v[150:153], v169 offset:32768
	ds_read_b128 v[154:157], v169 offset:34816
	ds_read_b128 v[158:161], v169 offset:36864
	ds_read_b128 v[162:165], v169 offset:38912
	ds_read_b128 v[170:173], v149
	ds_read_b128 v[174:177], v149 offset:2048
	s_add_u32 s4, s4, 0x80
	s_addc_u32 s5, s5, 0
	s_add_u32 s6, s6, 0x80
	s_addc_u32 s7, s7, 0
	s_cmp_eq_u32 s100, 1
	s_cbranch_scc1 .Lkl_1370_s9
	s_cmp_eq_u32 s101, 0
	s_cbranch_scc0 .Lkl_1370_s9
	v_readfirstlane_b32 s10, v140
	s_nop 3
	s_mul_i32 s8, s10, 8
	s_mul_i32 s9, s10, 0
	s_add_i32 s9, s9, 0x8000
	s_cmp_ge_u32 s10, 0x1000
	s_cselect_b32 s10, s9, s8
	s_xor_b32 s8, s3, 0x10000
	s_add_i32 s10, s10, s8
	s_add_i32 m0, s10, 0x1000
	s_add_u32 s8, s4, 0x1000
	s_addc_u32 s9, s5, 0x0
	global_load_lds_dwordx4 v238, s[8:9] offset:-4096
	s_add_u32 s8, s4, 0xc40
	s_addc_u32 s9, s5, 0x0
	global_load_lds_dwordx4 v238, s[8:9] offset:-3072
.Lkl_1370_s9:
	v_mfma_f32_16x16x32_bf16 v[30:33], v[222:225], v[192:195], v[30:33]
	v_mfma_f32_16x16x32_bf16 v[26:29], v[226:229], v[192:195], v[26:29]
	v_mfma_f32_16x16x32_bf16 v[22:25], v[230:233], v[192:195], v[22:25]
	v_mfma_f32_16x16x32_bf16 v[18:21], v[234:237], v[192:195], v[18:21]
	ds_read_b128 v[192:195], v149 offset:4096
	s_cmp_eq_u32 s100, 1
	s_cbranch_scc1 .Lkl_1370_s10
	s_cmp_eq_u32 s101, 0
	s_cbranch_scc0 .Lkl_1370_s10
	s_add_u32 s8, s4, 0x8800
	s_addc_u32 s9, s5, 0x0
	global_load_lds_dwordx4 v238, s[8:9] offset:-2048
	s_add_u32 s8, s4, 0x8440
	s_addc_u32 s9, s5, 0x0
	global_load_lds_dwordx4 v238, s[8:9] offset:-1024
.Lkl_1370_s10:
	v_mfma_f32_16x16x32_bf16 v[14:17], v[222:225], v[198:201], v[14:17]
	v_mfma_f32_16x16x32_bf16 v[10:13], v[226:229], v[198:201], v[10:13]
	v_mfma_f32_16x16x32_bf16 v[6:9], v[230:233], v[198:201], v[6:9]
	v_mfma_f32_16x16x32_bf16 v[2:5], v[234:237], v[198:201], v[2:5]
	ds_read_b128 v[198:201], v149 offset:6144
	s_cmp_eq_u32 s100, 1
	s_cbranch_scc1 .Lkl_1370_s11
	s_cmp_eq_u32 s101, 0
	s_cbranch_scc0 .Lkl_1370_s11
	s_add_u32 s8, s4, 0x10000
	s_addc_u32 s9, s5, 0x0
	global_load_lds_dwordx4 v238, s[8:9] offset:0
	s_add_u32 s8, s4, 0xfc40
	s_addc_u32 s9, s5, 0x0
	global_load_lds_dwordx4 v238, s[8:9] offset:1024

; #define WAIT_V0() asm volatile("s_waitcnt vmcnt(0)" ::: "memory")
; #define SBAR() __builtin_amdgcn_sched_barrier(0)
; template <int EPI>
; DEVI void gemm_tile(const u16* __restrict__ Ab, long lda, const u16* __restrict__ Bb, long ldb, int K, const EpiArgs& e,
;                     bool have0 = false, const u16* __restrict__ nA = nullptr, const u16* __restrict__ nB = nullptr) {
;     ...
;   f32x4 acc[8][4];
; #pragma unroll
;   for (int m = 0; m < 8; ++m)
; #pragma unroll
;     for (int n = 0; n < 4; ++n) acc[m][n] = f32x4{0.f, 0.f, 0.f, 0.f};
;   const int nt = K / BK;
;   if (!have0) GLDS_STAGE(0, 0);
;   WAIT_V0(); __syncthreads();
;   for (int t = 0; t < nt; ++t) {
;     const int cur = t & 1;
;     if (t + 1 < nt) GLDS_STAGE(cur ^ 1, t + 1);
;     else if (nA) {
; #pragma unroll
;       for (int i = 0; i < GL; ++i) {
;         __builtin_amdgcn_global_load_lds((const unsigned*)(nA + (long)i * 64 * lda + toffA), (unsigned*)(g_shm + wid * 1024 + i * 8192), 16, 0, 0);
;         __builtin_amdgcn_global_load_lds((const unsigned*)(nB + (long)i * 64 * ldb + toffB), (unsigned*)(g_shm + TILE_B + wid * 1024 + i * 8192), 16, 0, 0);
;       }
;     }
;     const char* sb = g_shm + cur * STAGE_B;
; #pragma unroll
;     for (int ks = 0; ks < 2; ++ks) {
;       bf16x8 Bf[4];
; #pragma unroll
;       for (int n = 0; n < 4; ++n) Bf[n] = *(const bf16x8*)(sb + b_base + n * 2048 + ks * 1024);
; #pragma unroll
;       for (int mh = 0; mh < 2; ++mh) {
;         bf16x8 At[4];
; #pragma unroll
;         for (int m = 0; m < 4; ++m) At[m] = *(const bf16x8*)(sb + a_base + (mh * 4 + m) * 2048 + ks * 1024);
;         __builtin_amdgcn_s_setprio(1);
; #pragma unroll
;         for (int m = 0; m < 4; ++m)
; #pragma unroll
;           for (int n = 0; n < 4; ++n) acc[mh * 4 + m][n] = __builtin_amdgcn_mfma_f32_16x16x32_bf16(Bf[n], At[m], acc[mh * 4 + m][n], 0, 0, 0);
;         __builtin_amdgcn_s_setprio(0);
;       }
;       SBAR();
;     }
;     if (t + 1 < nt) { WAIT_V0(); __syncthreads(); }
;   }
.LBB0_1404:
	s_and_b32 s26, s3, 0x10000
	v_or_b32_e32 v150, s26, v149
	v_add_u32_e32 v169, v150, v148
	v_or_b32_e32 v150, s26, v146
	v_add_u32_e32 v178, v150, v147
	ds_read_b128 v[150:153], v169 offset:32768
	ds_read_b128 v[154:157], v169 offset:34816
	ds_read_b128 v[158:161], v169 offset:36864
	ds_read_b128 v[162:165], v169 offset:38912
	ds_read_b128 v[170:173], v178
	ds_read_b128 v[174:177], v178 offset:2048
	ds_read_b128 v[192:195], v178 offset:4096
	ds_read_b128 v[198:201], v178 offset:6144
	v_writelane_b32 v240, s4, 0
	v_writelane_b32 v240, s5, 1
	v_writelane_b32 v240, s6, 2
	v_writelane_b32 v240, s7, 3
	v_writelane_b32 v240, s8, 4
	v_writelane_b32 v240, s9, 5
	v_writelane_b32 v240, s10, 6
	v_readfirstlane_b32 s4, v134
	v_readfirstlane_b32 s5, v135
	s_nop 1
	v_subrev_u32_e32 v238, s4, v134
	s_add_u32 s4, s4, s18
	s_addc_u32 s5, s5, s19
	v_readfirstlane_b32 s6, v136
	v_readfirstlane_b32 s7, v137
	s_nop 1
	v_subrev_u32_e32 v239, s6, v136
	s_add_u32 s6, s6, s18
	s_addc_u32 s7, s7, s19
	s_add_u32 s4, s4, s30
	s_addc_u32 s5, s5, s31
	s_add_u32 s6, s6, 0x1b80080
	s_addc_u32 s7, s7, 0
	v_readfirstlane_b32 s8, v143
	s_nop 3
	s_lshr_b32 s8, s8, 10
	s_mul_i32 s9, s8, 4
	s_mul_i32 s10, s8, 0
	s_add_i32 s10, s10, 16
	s_cmp_ge_u32 s8, 4
	s_cselect_b32 s10, s10, s9
	s_lshr_b32 s9, s8, 1
	s_sub_i32 s10, s10, s9
	s_lshl_b32 s10, s10, 4
	s_mul_hi_i32 s9, s10, 0x1600
	s_mul_i32 s10, s10, 0x1600
	s_and_b32 s8, s8, 1
	s_lshl_b32 s8, s8, 6
	s_sub_u32 s10, s10, s8
	s_subb_u32 s9, s9, 0
	s_add_u32 s4, s4, s10
	s_addc_u32 s5, s5, s9
	s_add_u32 s6, s6, s10
	s_addc_u32 s7, s7, s9
	s_cmp_eq_u32 s101, 0
	s_cbranch_scc0 .Lkl_1404_s1
	v_readfirstlane_b32 s10, v143
	s_nop 3
	s_mul_i32 s8, s10, 8
	s_mul_i32 s9, s10, 0
	s_add_i32 s9, s9, 0x8000
	s_cmp_ge_u32 s10, 0x1000
	s_cselect_b32 s10, s9, s8
	s_xor_b32 s8, s26, 0x10000
	s_add_i32 s10, s10, s8
	s_add_i32 m0, s10, 0x1000
	s_add_u32 s8, s4, 0x1000
	s_addc_u32 s9, s5, 0x0
	global_load_lds_dwordx4 v238, s[8:9] offset:-4096
	s_add_u32 s8, s4, 0xc40
	s_addc_u32 s9, s5, 0x0
	global_load_lds_dwordx4 v238, s[8:9] offset:-3072

; #define WAIT_V0() asm volatile("s_waitcnt vmcnt(0)" ::: "memory")
; #define SBAR() __builtin_amdgcn_sched_barrier(0)
; template <int EPI>
; DEVI void gemm_tile(const u16* __restrict__ Ab, long lda, const u16* __restrict__ Bb, long ldb, int K, const EpiArgs& e,
;                     bool have0 = false, const u16* __restrict__ nA = nullptr, const u16* __restrict__ nB = nullptr) {
;     ...
;   f32x4 acc[8][4];
; #pragma unroll
;   for (int m = 0; m < 8; ++m)
; #pragma unroll
;     for (int n = 0; n < 4; ++n) acc[m][n] = f32x4{0.f, 0.f, 0.f, 0.f};
;   const int nt = K / BK;
;   if (!have0) GLDS_STAGE(0, 0);
;   WAIT_V0(); __syncthreads();
;   for (int t = 0; t < nt; ++t) {
;     const int cur = t & 1;
;     if (t + 1 < nt) GLDS_STAGE(cur ^ 1, t + 1);
;     else if (nA) {
; #pragma unroll
;       for (int i = 0; i < GL; ++i) {
;         __builtin_amdgcn_global_load_lds((const unsigned*)(nA + (long)i * 64 * lda + toffA), (unsigned*)(g_shm + wid * 1024 + i * 8192), 16, 0, 0);
;         __builtin_amdgcn_global_load_lds((const unsigned*)(nB + (long)i * 64 * ldb + toffB), (unsigned*)(g_shm + TILE_B + wid * 1024 + i * 8192), 16, 0, 0);
;       }
;     }
;     const char* sb = g_shm + cur * STAGE_B;
; #pragma unroll
;     for (int ks = 0; ks < 2; ++ks) {
;       bf16x8 Bf[4];
; #pragma unroll
;       for (int n = 0; n < 4; ++n) Bf[n] = *(const bf16x8*)(sb + b_base + n * 2048 + ks * 1024);
; #pragma unroll
;       for (int mh = 0; mh < 2; ++mh) {
;         bf16x8 At[4];
; #pragma unroll
;         for (int m = 0; m < 4; ++m) At[m] = *(const bf16x8*)(sb + a_base + (mh * 4 + m) * 2048 + ks * 1024);
;         __builtin_amdgcn_s_setprio(1);
; #pragma unroll
;         for (int m = 0; m < 4; ++m)
; #pragma unroll
;           for (int n = 0; n < 4; ++n) acc[mh * 4 + m][n] = __builtin_amdgcn_mfma_f32_16x16x32_bf16(Bf[n], At[m], acc[mh * 4 + m][n], 0, 0, 0);
;         __builtin_amdgcn_s_setprio(0);
;       }
;       SBAR();
;     }
;     if (t + 1 < nt) { WAIT_V0(); __syncthreads(); }
;   }
.Lkl_1404_s5:
	s_waitcnt lgkmcnt(5)
	v_mfma_f32_16x16x32_bf16 v[94:97], v[150:153], v[192:195], v[94:97]
	v_mfma_f32_16x16x32_bf16 v[90:93], v[154:157], v[192:195], v[90:93]
	v_mfma_f32_16x16x32_bf16 v[86:89], v[158:161], v[192:195], v[86:89]
	v_mfma_f32_16x16x32_bf16 v[82:85], v[162:165], v[192:195], v[82:85]
	ds_read_b128 v[192:195], v178 offset:12288
	ds_read_b128 v[230:233], v169 offset:37888
	s_cmp_eq_u32 s101, 0
	s_cbranch_scc0 .Lkl_1404_s6
	s_add_u32 s8, s6, 0x16800
	s_addc_u32 s9, s7, 0x0
	global_load_lds_dwordx4 v239, s[8:9] offset:-2048
	s_add_u32 s8, s6, 0x16440
	s_addc_u32 s9, s7, 0x0
	global_load_lds_dwordx4 v239, s[8:9] offset:-1024
.Lkl_1404_s6:
	s_waitcnt lgkmcnt(6)
	v_mfma_f32_16x16x32_bf16 v[78:81], v[150:153], v[198:201], v[78:81]
	v_mfma_f32_16x16x32_bf16 v[74:77], v[154:157], v[198:201], v[74:77]
	v_mfma_f32_16x16x32_bf16 v[70:73], v[158:161], v[198:201], v[70:73]
	v_mfma_f32_16x16x32_bf16 v[66:69], v[162:165], v[198:201], v[66:69]
	ds_read_b128 v[198:201], v178 offset:14336
	ds_read_b128 v[234:237], v169 offset:39936
	s_cmp_eq_u32 s101, 0
	s_cbranch_scc0 .Lkl_1404_s7
	s_add_u32 s8, s6, 0x2c000
	s_addc_u32 s9, s7, 0x0
	global_load_lds_dwordx4 v239, s[8:9] offset:0
	s_add_u32 s8, s6, 0x2bc40
	s_addc_u32 s9, s7, 0x0
	global_load_lds_dwordx4 v239, s[8:9] offset:1024

; #define WAIT_V0() asm volatile("s_waitcnt vmcnt(0)" ::: "memory")
; #define SBAR() __builtin_amdgcn_sched_barrier(0)
; template <int EPI>
; DEVI void gemm_tile(const u16* __restrict__ Ab, long lda, const u16* __restrict__ Bb, long ldb, int K, const EpiArgs& e,
;                     bool have0 = false, const u16* __restrict__ nA = nullptr, const u16* __restrict__ nB = nullptr) {
;     ...
;   for (int t = 0; t < nt; ++t) {
;     const int cur = t & 1;
;     if (t + 1 < nt) GLDS_STAGE(cur ^ 1, t + 1);
;     else if (nA) {
; #pragma unroll
;       for (int i = 0; i < GL; ++i) {
;         __builtin_amdgcn_global_load_lds((const unsigned*)(nA + (long)i * 64 * lda + toffA), (unsigned*)(g_shm + wid * 1024 + i * 8192), 16, 0, 0);
;         __builtin_amdgcn_global_load_lds((const unsigned*)(nB + (long)i * 64 * ldb + toffB), (unsigned*)(g_shm + TILE_B + wid * 1024 + i * 8192), 16, 0, 0);
;       }
;     }
;     const char* sb = g_shm + cur * STAGE_B;
; #pragma unroll
;     for (int ks = 0; ks < 2; ++ks) {
;       bf16x8 Bf[4];
; #pragma unroll
;       for (int n = 0; n < 4; ++n) Bf[n] = *(const bf16x8*)(sb + b_base + n * 2048 + ks * 1024);
; #pragma unroll
;       for (int mh = 0; mh < 2; ++mh) {
;         bf16x8 At[4];
; #pragma unroll
;         for (int m = 0; m < 4; ++m) At[m] = *(const bf16x8*)(sb + a_base + (mh * 4 + m) * 2048 + ks * 1024);
;         __builtin_amdgcn_s_setprio(1);
; #pragma unroll
;         for (int m = 0; m < 4; ++m)
; #pragma unroll
;           for (int n = 0; n < 4; ++n) acc[mh * 4 + m][n] = __builtin_amdgcn_mfma_f32_16x16x32_bf16(Bf[n], At[m], acc[mh * 4 + m][n], 0, 0, 0);
;         __builtin_amdgcn_s_setprio(0);
;       }
;       SBAR();
;     }
;     if (t + 1 < nt) { WAIT_V0(); __syncthreads(); }
;   }
.Lkl_1404_s8:
	s_waitcnt lgkmcnt(6)
	v_mfma_f32_16x16x32_bf16 v[46:49], v[150:153], v[174:177], v[46:49]
	v_mfma_f32_16x16x32_bf16 v[42:45], v[154:157], v[174:177], v[42:45]
	v_mfma_f32_16x16x32_bf16 v[38:41], v[158:161], v[174:177], v[38:41]
	v_mfma_f32_16x16x32_bf16 v[34:37], v[162:165], v[174:177], v[34:37]
	ds_read_b128 v[174:177], v178 offset:3072
	s_waitcnt lgkmcnt(5)
	v_mfma_f32_16x16x32_bf16 v[30:33], v[150:153], v[192:195], v[30:33]
	v_mfma_f32_16x16x32_bf16 v[26:29], v[154:157], v[192:195], v[26:29]
	v_mfma_f32_16x16x32_bf16 v[22:25], v[158:161], v[192:195], v[22:25]
	v_mfma_f32_16x16x32_bf16 v[18:21], v[162:165], v[192:195], v[18:21]
	ds_read_b128 v[192:195], v178 offset:5120
	s_waitcnt lgkmcnt(4)
	v_mfma_f32_16x16x32_bf16 v[14:17], v[150:153], v[198:201], v[14:17]
	v_mfma_f32_16x16x32_bf16 v[10:13], v[154:157], v[198:201], v[10:13]
	v_mfma_f32_16x16x32_bf16 v[6:9], v[158:161], v[198:201], v[6:9]
	v_mfma_f32_16x16x32_bf16 v[2:5], v[162:165], v[198:201], v[2:5]
	ds_read_b128 v[198:201], v178 offset:7168
	s_waitcnt lgkmcnt(3)
	v_mfma_f32_16x16x32_bf16 v[126:129], v[222:225], v[170:173], v[126:129]
	v_mfma_f32_16x16x32_bf16 v[122:125], v[226:229], v[170:173], v[122:125]
	v_mfma_f32_16x16x32_bf16 v[118:121], v[230:233], v[170:173], v[118:121]
	v_mfma_f32_16x16x32_bf16 v[114:117], v[234:237], v[170:173], v[114:117]
	ds_read_b128 v[170:173], v178 offset:9216
	s_waitcnt lgkmcnt(3)
	v_mfma_f32_16x16x32_bf16 v[110:113], v[222:225], v[174:177], v[110:113]
	v_mfma_f32_16x16x32_bf16 v[106:109], v[226:229], v[174:177], v[106:109]
	v_mfma_f32_16x16x32_bf16 v[102:105], v[230:233], v[174:177], v[102:105]
	v_mfma_f32_16x16x32_bf16 v[98:101], v[234:237], v[174:177], v[98:101]
	ds_read_b128 v[174:177], v178 offset:11264
	s_waitcnt lgkmcnt(3)
	v_mfma_f32_16x16x32_bf16 v[94:97], v[222:225], v[192:195], v[94:97]
	v_mfma_f32_16x16x32_bf16 v[90:93], v[226:229], v[192:195], v[90:93]
	v_mfma_f32_16x16x32_bf16 v[86:89], v[230:233], v[192:195], v[86:89]
	v_mfma_f32_16x16x32_bf16 v[82:85], v[234:237], v[192:195], v[82:85]
	ds_read_b128 v[192:195], v178 offset:13312
	s_waitcnt lgkmcnt(3)
	v_mfma_f32_16x16x32_bf16 v[78:81], v[222:225], v[198:201], v[78:81]
	v_mfma_f32_16x16x32_bf16 v[74:77], v[226:229], v[198:201], v[74:77]
	v_mfma_f32_16x16x32_bf16 v[70:73], v[230:233], v[198:201], v[70:73]
	v_mfma_f32_16x16x32_bf16 v[66:69], v[234:237], v[198:201], v[66:69]
	ds_read_b128 v[198:201], v178 offset:15360
	s_waitcnt lgkmcnt(3)
	v_mfma_f32_16x16x32_bf16 v[62:65], v[222:225], v[170:173], v[62:65]
	v_mfma_f32_16x16x32_bf16 v[58:61], v[226:229], v[170:173], v[58:61]
	v_mfma_f32_16x16x32_bf16 v[54:57], v[230:233], v[170:173], v[54:57]
	v_mfma_f32_16x16x32_bf16 v[50:53], v[234:237], v[170:173], v[50:53]
	s_waitcnt lgkmcnt(2)
	v_mfma_f32_16x16x32_bf16 v[46:49], v[222:225], v[174:177], v[46:49]
	v_mfma_f32_16x16x32_bf16 v[42:45], v[226:229], v[174:177], v[42:45]
	v_mfma_f32_16x16x32_bf16 v[38:41], v[230:233], v[174:177], v[38:41]
	v_mfma_f32_16x16x32_bf16 v[34:37], v[234:237], v[174:177], v[34:37]
	s_waitcnt lgkmcnt(0)
	s_waitcnt vmcnt(0)
	s_add_u32 s18, s18, 0x80
	s_addc_u32 s19, s19, 0
	s_add_i32 s3, s3, 0x10000
	s_cmpk_eq_i32 s18, 0x1580
	s_waitcnt vmcnt(0)
	s_barrier
	s_cselect_b32 s100, 1, 0
	s_and_b32 s26, s3, 0x10000
	v_or_b32_e32 v150, s26, v149
	v_add_u32_e32 v169, v150, v148
	v_or_b32_e32 v150, s26, v146
	v_add_u32_e32 v178, v150, v147
	ds_read_b128 v[150:153], v169 offset:32768
	ds_read_b128 v[154:157], v169 offset:34816
	ds_read_b128 v[158:161], v169 offset:36864
	ds_read_b128 v[162:165], v169 offset:38912
	ds_read_b128 v[170:173], v178
	ds_read_b128 v[174:177], v178 offset:2048
	s_add_u32 s4, s4, 0x80
	s_addc_u32 s5, s5, 0
	s_add_u32 s6, s6, 0x80
	s_addc_u32 s7, s7, 0
	s_cmp_eq_u32 s100, 1
	s_cbranch_scc1 .Lkl_1404_s9
	s_cmp_eq_u32 s101, 0
	s_cbranch_scc0 .Lkl_1404_s9
	v_readfirstlane_b32 s10, v143
	s_nop 3
	s_mul_i32 s8, s10, 8
	s_mul_i32 s9, s10, 0
	s_add_i32 s9, s9, 0x8000
	s_cmp_ge_u32 s10, 0x1000
	s_cselect_b32 s10, s9, s8
	s_xor_b32 s8, s26, 0x10000
	s_add_i32 s10, s10, s8
	s_add_i32 m0, s10, 0x1000
	s_add_u32 s8, s4, 0x1000
	s_addc_u32 s9, s5, 0x0
	global_load_lds_dwordx4 v238, s[8:9] offset:-4096
	s_add_u32 s8, s4, 0xc40
	s_addc_u32 s9, s5, 0x0
	global_load_lds_dwordx4 v238, s[8:9] offset:-3072
.Lkl_1404_s9:
	v_mfma_f32_16x16x32_bf16 v[30:33], v[222:225], v[192:195], v[30:33]
	v_mfma_f32_16x16x32_bf16 v[26:29], v[226:229], v[192:195], v[26:29]
	v_mfma_f32_16x16x32_bf16 v[22:25], v[230:233], v[192:195], v[22:25]
	v_mfma_f32_16x16x32_bf16 v[18:21], v[234:237], v[192:195], v[18:21]
	ds_read_b128 v[192:195], v178 offset:4096
	s_cmp_eq_u32 s100, 1
	s_cbranch_scc1 .Lkl_1404_s10
	s_cmp_eq_u32 s101, 0
	s_cbranch_scc0 .Lkl_1404_s10
	s_add_u32 s8, s4, 0x16800
	s_addc_u32 s9, s5, 0x0
	global_load_lds_dwordx4 v238, s[8:9] offset:-2048
	s_add_u32 s8, s4, 0x16440
	s_addc_u32 s9, s5, 0x0
	global_load_lds_dwordx4 v238, s[8:9] offset:-1024
.Lkl_1404_s10:
	v_mfma_f32_16x16x32_bf16 v[14:17], v[222:225], v[198:201], v[14:17]
	v_mfma_f32_16x16x32_bf16 v[10:13], v[226:229], v[198:201], v[10:13]
	v_mfma_f32_16x16x32_bf16 v[6:9], v[230:233], v[198:201], v[6:9]
	v_mfma_f32_16x16x32_bf16 v[2:5], v[234:237], v[198:201], v[2:5]
	ds_read_b128 v[198:201], v178 offset:6144
	s_cmp_eq_u32 s100, 1
	s_cbranch_scc1 .Lkl_1404_s11
	s_cmp_eq_u32 s101, 0
	s_cbranch_scc0 .Lkl_1404_s11
	s_add_u32 s8, s4, 0x2c000
	s_addc_u32 s9, s5, 0x0
	global_load_lds_dwordx4 v238, s[8:9] offset:0
	s_add_u32 s8, s4, 0x2bc40
	s_addc_u32 s9, s5, 0x0
	global_load_lds_dwordx4 v238, s[8:9] offset:1024
